# K-loop counted waits relaxed: phase 4/8 vmcnt(6)->vmcnt(8), new vmcnt(10) in phase 2/6, so the two latest-staged A half-tiles get two more phases of flight time
# speedup vs baseline: 1.0528x; 1.0014x over previous
.Lg131_noy:
	ds_read_b128 v[152:155], v149
	ds_read_b128 v[156:159], v149 offset:1024
	ds_read_b128 v[160:163], v149 offset:2048
	ds_read_b128 v[164:167], v149 offset:3072
	s_add_u32 s26, s20, 0xfffc0080
	s_addc_u32 s27, s21, -1
	s_cmp_eq_u32 s57, 12
	s_cselect_b32 s29, s13, s27
	s_cselect_b32 s28, s53, s26
	s_cselect_b32 s27, s11, s56
	s_cselect_b32 s26, s54, s55
	s_add_i32 m0, s19, 0xc000
	ds_read_b128 v[168:171], v150
	ds_read_b128 v[172:175], v150 offset:1024
	ds_read_b128 v[176:179], v150 offset:2048
	ds_read_b128 v[180:183], v150 offset:3072
	ds_read_b128 v[184:187], v150 offset:4096
	ds_read_b128 v[188:191], v150 offset:5120
	ds_read_b128 v[192:195], v150 offset:6144
	ds_read_b128 v[196:199], v150 offset:7168
	global_load_lds_dwordx4 v136, s[20:21]
	s_add_i32 m0, s19, 0xe000
	s_nop 0
	global_load_lds_dwordx4 v138, s[20:21]
	s_waitcnt lgkmcnt(8)
	s_barrier
	s_waitcnt lgkmcnt(0)
	s_setprio 1
	s_waitcnt lgkmcnt(0)
	v_mfma_f32_16x16x32_bf16 v[124:127], v[152:155], v[168:171], 0
	v_mfma_f32_16x16x32_bf16 v[120:123], v[160:163], v[168:171], 0
	v_mfma_f32_16x16x32_bf16 v[108:111], v[152:155], v[176:179], 0
	v_mfma_f32_16x16x32_bf16 v[104:107], v[160:163], v[176:179], 0
	v_mfma_f32_16x16x32_bf16 v[92:95], v[152:155], v[184:187], 0
	v_mfma_f32_16x16x32_bf16 v[88:91], v[160:163], v[184:187], 0
	v_mfma_f32_16x16x32_bf16 v[76:79], v[152:155], v[192:195], 0
	v_mfma_f32_16x16x32_bf16 v[72:75], v[160:163], v[192:195], 0
	v_mfma_f32_16x16x32_bf16 v[124:127], v[156:159], v[172:175], v[124:127]
	v_mfma_f32_16x16x32_bf16 v[120:123], v[164:167], v[172:175], v[120:123]
	v_mfma_f32_16x16x32_bf16 v[108:111], v[156:159], v[180:183], v[108:111]
	v_mfma_f32_16x16x32_bf16 v[104:107], v[164:167], v[180:183], v[104:107]
	v_mfma_f32_16x16x32_bf16 v[92:95], v[156:159], v[188:191], v[92:95]
	v_mfma_f32_16x16x32_bf16 v[88:91], v[164:167], v[188:191], v[88:91]
	v_mfma_f32_16x16x32_bf16 v[76:79], v[156:159], v[196:199], v[76:79]
	v_mfma_f32_16x16x32_bf16 v[72:75], v[164:167], v[196:199], v[72:75]
	s_setprio 0
	s_barrier
	s_add_i32 s58, s47, s38
	s_add_u32 s80, s26, 0x80
	s_addc_u32 s81, s27, 0
	s_mov_b32 m0, s58
	ds_read_b128 v[200:203], v151
	ds_read_b128 v[204:207], v151 offset:1024
	ds_read_b128 v[208:211], v151 offset:2048
	ds_read_b128 v[212:215], v151 offset:3072
	global_load_lds_dwordx4 v132, s[26:27]
	s_add_i32 m0, s58, 0x2000
	s_nop 0
	global_load_lds_dwordx4 v128, s[26:27]
	s_waitcnt vmcnt(10)
	s_barrier
	s_waitcnt lgkmcnt(0)
	s_setprio 1
	s_waitcnt lgkmcnt(0)
	v_mfma_f32_16x16x32_bf16 v[116:119], v[200:203], v[168:171], 0
	v_mfma_f32_16x16x32_bf16 v[112:115], v[208:211], v[168:171], 0
	v_mfma_f32_16x16x32_bf16 v[100:103], v[200:203], v[176:179], 0
	v_mfma_f32_16x16x32_bf16 v[96:99], v[208:211], v[176:179], 0
	v_mfma_f32_16x16x32_bf16 v[84:87], v[200:203], v[184:187], 0
	v_mfma_f32_16x16x32_bf16 v[80:83], v[208:211], v[184:187], 0
	v_mfma_f32_16x16x32_bf16 v[68:71], v[200:203], v[192:195], 0
	v_mfma_f32_16x16x32_bf16 v[64:67], v[208:211], v[192:195], 0
	v_mfma_f32_16x16x32_bf16 v[116:119], v[204:207], v[172:175], v[116:119]
	v_mfma_f32_16x16x32_bf16 v[112:115], v[212:215], v[172:175], v[112:115]
	v_mfma_f32_16x16x32_bf16 v[100:103], v[204:207], v[180:183], v[100:103]
	v_mfma_f32_16x16x32_bf16 v[96:99], v[212:215], v[180:183], v[96:99]
	v_mfma_f32_16x16x32_bf16 v[84:87], v[204:207], v[188:191], v[84:87]
	v_mfma_f32_16x16x32_bf16 v[80:83], v[212:215], v[188:191], v[80:83]
	v_mfma_f32_16x16x32_bf16 v[68:71], v[204:207], v[196:199], v[68:71]
	v_mfma_f32_16x16x32_bf16 v[64:67], v[212:215], v[196:199], v[64:67]
	s_setprio 0
	s_mov_b32 m0, s19
	s_add_u32 s82, s28, 0x80
	s_addc_u32 s83, s29, 0
	s_barrier
	ds_read_b128 v[168:171], v150 offset:16384
	ds_read_b128 v[172:175], v150 offset:17408
	ds_read_b128 v[176:179], v150 offset:18432
	ds_read_b128 v[180:183], v150 offset:19456
	ds_read_b128 v[184:187], v150 offset:20480
	ds_read_b128 v[188:191], v150 offset:21504
	ds_read_b128 v[192:195], v150 offset:22528
	ds_read_b128 v[196:199], v150 offset:23552
	global_load_lds_dwordx4 v134, s[28:29]
	s_mov_b32 m0, s42
	s_nop 0
	global_load_lds_dwordx4 v130, s[28:29]
	s_barrier
	s_waitcnt lgkmcnt(0)
	s_setprio 1
	s_waitcnt lgkmcnt(0)
	v_mfma_f32_16x16x32_bf16 v[60:63], v[152:155], v[168:171], 0
	v_mfma_f32_16x16x32_bf16 v[56:59], v[160:163], v[168:171], 0
	v_mfma_f32_16x16x32_bf16 v[44:47], v[152:155], v[176:179], 0
	v_mfma_f32_16x16x32_bf16 v[40:43], v[160:163], v[176:179], 0
	v_mfma_f32_16x16x32_bf16 v[28:31], v[152:155], v[184:187], 0
	v_mfma_f32_16x16x32_bf16 v[24:27], v[160:163], v[184:187], 0
	v_mfma_f32_16x16x32_bf16 v[12:15], v[152:155], v[192:195], 0
	v_mfma_f32_16x16x32_bf16 v[8:11], v[160:163], v[192:195], 0
	v_mfma_f32_16x16x32_bf16 v[60:63], v[156:159], v[172:175], v[60:63]
	v_mfma_f32_16x16x32_bf16 v[56:59], v[164:167], v[172:175], v[56:59]
	v_mfma_f32_16x16x32_bf16 v[44:47], v[156:159], v[180:183], v[44:47]
	v_mfma_f32_16x16x32_bf16 v[40:43], v[164:167], v[180:183], v[40:43]
	v_mfma_f32_16x16x32_bf16 v[28:31], v[156:159], v[188:191], v[28:31]
	v_mfma_f32_16x16x32_bf16 v[24:27], v[164:167], v[188:191], v[24:27]
	v_mfma_f32_16x16x32_bf16 v[12:15], v[156:159], v[196:199], v[12:15]
	v_mfma_f32_16x16x32_bf16 v[8:11], v[164:167], v[196:199], v[8:11]
	s_setprio 0
	s_barrier
	s_add_u32 s58, s26, 0x40000
	s_addc_u32 s59, s27, 0
	s_add_i32 s60, s48, s38
	s_mov_b32 m0, s60
	s_nop 0
	global_load_lds_dwordx4 v132, s[58:59]
	s_add_i32 m0, s60, 0x2000
	s_nop 0
	global_load_lds_dwordx4 v128, s[58:59]
	s_waitcnt vmcnt(8)
	s_barrier
	s_setprio 1
	v_mfma_f32_16x16x32_bf16 v[52:55], v[200:203], v[168:171], 0
	v_mfma_f32_16x16x32_bf16 v[48:51], v[208:211], v[168:171], 0
	v_mfma_f32_16x16x32_bf16 v[36:39], v[200:203], v[176:179], 0
	v_mfma_f32_16x16x32_bf16 v[32:35], v[208:211], v[176:179], 0
	v_mfma_f32_16x16x32_bf16 v[20:23], v[200:203], v[184:187], 0
	v_mfma_f32_16x16x32_bf16 v[16:19], v[208:211], v[184:187], 0
	v_mfma_f32_16x16x32_bf16 v[4:7], v[200:203], v[192:195], 0
	v_mfma_f32_16x16x32_bf16 v[0:3], v[208:211], v[192:195], 0
	v_mfma_f32_16x16x32_bf16 v[52:55], v[204:207], v[172:175], v[52:55]
	v_mfma_f32_16x16x32_bf16 v[48:51], v[212:215], v[172:175], v[48:51]
	v_mfma_f32_16x16x32_bf16 v[36:39], v[204:207], v[180:183], v[36:39]
	v_mfma_f32_16x16x32_bf16 v[32:35], v[212:215], v[180:183], v[32:35]
	v_mfma_f32_16x16x32_bf16 v[20:23], v[204:207], v[188:191], v[20:23]
	v_mfma_f32_16x16x32_bf16 v[16:19], v[212:215], v[188:191], v[16:19]
	v_mfma_f32_16x16x32_bf16 v[4:7], v[204:207], v[196:199], v[4:7]
	v_mfma_f32_16x16x32_bf16 v[0:3], v[212:215], v[196:199], v[0:3]
	s_setprio 0
	s_add_i32 s58, 0, 0x18000
	v_add_u32_e32 v164, s58, v145
	s_barrier
	s_branch .Lg131_mid
.LBB0_131:
	ds_read_b128 v[152:155], v149
	ds_read_b128 v[156:159], v149 offset:1024
	ds_read_b128 v[160:163], v149 offset:2048
	ds_read_b128 v[164:167], v149 offset:3072
	s_add_u32 s26, s20, 0xfffc0080
	s_addc_u32 s27, s21, -1
	s_cmp_eq_u32 s57, 12
	s_cselect_b32 s29, s13, s27
	s_cselect_b32 s28, s53, s26
	s_cselect_b32 s27, s11, s56
	s_cselect_b32 s26, s54, s55
	s_add_i32 m0, s19, 0xc000
	ds_read_b128 v[168:171], v150
	ds_read_b128 v[172:175], v150 offset:1024
	ds_read_b128 v[176:179], v150 offset:2048
	ds_read_b128 v[180:183], v150 offset:3072
	ds_read_b128 v[184:187], v150 offset:4096
	ds_read_b128 v[188:191], v150 offset:5120
	ds_read_b128 v[192:195], v150 offset:6144
	ds_read_b128 v[196:199], v150 offset:7168
	global_load_lds_dwordx4 v136, s[20:21]
	s_add_i32 m0, s19, 0xe000
	s_nop 0
	global_load_lds_dwordx4 v138, s[20:21]
	s_waitcnt lgkmcnt(8)
	s_barrier
	s_waitcnt lgkmcnt(0)
	s_setprio 1
	s_waitcnt lgkmcnt(0)
	v_mfma_f32_16x16x32_bf16 v[124:127], v[152:155], v[168:171], v[124:127]
	v_mfma_f32_16x16x32_bf16 v[120:123], v[160:163], v[168:171], v[120:123]
	v_mfma_f32_16x16x32_bf16 v[108:111], v[152:155], v[176:179], v[108:111]
	v_mfma_f32_16x16x32_bf16 v[104:107], v[160:163], v[176:179], v[104:107]
	v_mfma_f32_16x16x32_bf16 v[92:95], v[152:155], v[184:187], v[92:95]
	v_mfma_f32_16x16x32_bf16 v[88:91], v[160:163], v[184:187], v[88:91]
	v_mfma_f32_16x16x32_bf16 v[76:79], v[152:155], v[192:195], v[76:79]
	v_mfma_f32_16x16x32_bf16 v[72:75], v[160:163], v[192:195], v[72:75]
	v_mfma_f32_16x16x32_bf16 v[124:127], v[156:159], v[172:175], v[124:127]
	v_mfma_f32_16x16x32_bf16 v[120:123], v[164:167], v[172:175], v[120:123]
	v_mfma_f32_16x16x32_bf16 v[108:111], v[156:159], v[180:183], v[108:111]
	v_mfma_f32_16x16x32_bf16 v[104:107], v[164:167], v[180:183], v[104:107]
	v_mfma_f32_16x16x32_bf16 v[92:95], v[156:159], v[188:191], v[92:95]
	v_mfma_f32_16x16x32_bf16 v[88:91], v[164:167], v[188:191], v[88:91]
	v_mfma_f32_16x16x32_bf16 v[76:79], v[156:159], v[196:199], v[76:79]
	v_mfma_f32_16x16x32_bf16 v[72:75], v[164:167], v[196:199], v[72:75]
	s_setprio 0
	s_barrier
	s_add_i32 s58, s47, s38
	s_add_u32 s80, s26, 0x80
	s_addc_u32 s81, s27, 0
	s_mov_b32 m0, s58
	ds_read_b128 v[200:203], v151
	ds_read_b128 v[204:207], v151 offset:1024
	ds_read_b128 v[208:211], v151 offset:2048
	ds_read_b128 v[212:215], v151 offset:3072
	global_load_lds_dwordx4 v132, s[26:27]
	s_add_i32 m0, s58, 0x2000
	s_nop 0
	global_load_lds_dwordx4 v128, s[26:27]
	s_waitcnt vmcnt(10)
	s_barrier
	s_waitcnt lgkmcnt(0)
	s_setprio 1
	s_waitcnt lgkmcnt(0)
	v_mfma_f32_16x16x32_bf16 v[116:119], v[200:203], v[168:171], v[116:119]
	v_mfma_f32_16x16x32_bf16 v[112:115], v[208:211], v[168:171], v[112:115]
	v_mfma_f32_16x16x32_bf16 v[100:103], v[200:203], v[176:179], v[100:103]
	v_mfma_f32_16x16x32_bf16 v[96:99], v[208:211], v[176:179], v[96:99]
	v_mfma_f32_16x16x32_bf16 v[84:87], v[200:203], v[184:187], v[84:87]
	v_mfma_f32_16x16x32_bf16 v[80:83], v[208:211], v[184:187], v[80:83]
	v_mfma_f32_16x16x32_bf16 v[68:71], v[200:203], v[192:195], v[68:71]
	v_mfma_f32_16x16x32_bf16 v[64:67], v[208:211], v[192:195], v[64:67]
	v_mfma_f32_16x16x32_bf16 v[116:119], v[204:207], v[172:175], v[116:119]
	v_mfma_f32_16x16x32_bf16 v[112:115], v[212:215], v[172:175], v[112:115]
	v_mfma_f32_16x16x32_bf16 v[100:103], v[204:207], v[180:183], v[100:103]
	v_mfma_f32_16x16x32_bf16 v[96:99], v[212:215], v[180:183], v[96:99]
	v_mfma_f32_16x16x32_bf16 v[84:87], v[204:207], v[188:191], v[84:87]
	v_mfma_f32_16x16x32_bf16 v[80:83], v[212:215], v[188:191], v[80:83]
	v_mfma_f32_16x16x32_bf16 v[68:71], v[204:207], v[196:199], v[68:71]
	v_mfma_f32_16x16x32_bf16 v[64:67], v[212:215], v[196:199], v[64:67]
	s_setprio 0
	s_mov_b32 m0, s19
	s_add_u32 s82, s28, 0x80
	s_addc_u32 s83, s29, 0
	s_barrier
	ds_read_b128 v[168:171], v150 offset:16384
	ds_read_b128 v[172:175], v150 offset:17408
	ds_read_b128 v[176:179], v150 offset:18432
	ds_read_b128 v[180:183], v150 offset:19456
	ds_read_b128 v[184:187], v150 offset:20480
	ds_read_b128 v[188:191], v150 offset:21504
	ds_read_b128 v[192:195], v150 offset:22528
	ds_read_b128 v[196:199], v150 offset:23552
	global_load_lds_dwordx4 v134, s[28:29]
	s_mov_b32 m0, s42
	s_nop 0
	global_load_lds_dwordx4 v130, s[28:29]
	s_barrier
	s_waitcnt lgkmcnt(0)
	s_setprio 1
	s_waitcnt lgkmcnt(0)
	v_mfma_f32_16x16x32_bf16 v[60:63], v[152:155], v[168:171], v[60:63]
	v_mfma_f32_16x16x32_bf16 v[56:59], v[160:163], v[168:171], v[56:59]
	v_mfma_f32_16x16x32_bf16 v[44:47], v[152:155], v[176:179], v[44:47]
	v_mfma_f32_16x16x32_bf16 v[40:43], v[160:163], v[176:179], v[40:43]
	v_mfma_f32_16x16x32_bf16 v[28:31], v[152:155], v[184:187], v[28:31]
	v_mfma_f32_16x16x32_bf16 v[24:27], v[160:163], v[184:187], v[24:27]
	v_mfma_f32_16x16x32_bf16 v[12:15], v[152:155], v[192:195], v[12:15]
	v_mfma_f32_16x16x32_bf16 v[8:11], v[160:163], v[192:195], v[8:11]
	v_mfma_f32_16x16x32_bf16 v[60:63], v[156:159], v[172:175], v[60:63]
	v_mfma_f32_16x16x32_bf16 v[56:59], v[164:167], v[172:175], v[56:59]
	v_mfma_f32_16x16x32_bf16 v[44:47], v[156:159], v[180:183], v[44:47]
	v_mfma_f32_16x16x32_bf16 v[40:43], v[164:167], v[180:183], v[40:43]
	v_mfma_f32_16x16x32_bf16 v[28:31], v[156:159], v[188:191], v[28:31]
	v_mfma_f32_16x16x32_bf16 v[24:27], v[164:167], v[188:191], v[24:27]
	v_mfma_f32_16x16x32_bf16 v[12:15], v[156:159], v[196:199], v[12:15]
	v_mfma_f32_16x16x32_bf16 v[8:11], v[164:167], v[196:199], v[8:11]
	s_setprio 0
	s_barrier
	s_add_u32 s58, s26, 0x40000
	s_addc_u32 s59, s27, 0
	s_add_i32 s60, s48, s38
	s_mov_b32 m0, s60
	s_nop 0
	global_load_lds_dwordx4 v132, s[58:59]
	s_add_i32 m0, s60, 0x2000
	s_nop 0
	global_load_lds_dwordx4 v128, s[58:59]
	s_waitcnt vmcnt(8)
	s_barrier
	s_setprio 1
	v_mfma_f32_16x16x32_bf16 v[52:55], v[200:203], v[168:171], v[52:55]
	v_mfma_f32_16x16x32_bf16 v[48:51], v[208:211], v[168:171], v[48:51]
	v_mfma_f32_16x16x32_bf16 v[36:39], v[200:203], v[176:179], v[36:39]
	v_mfma_f32_16x16x32_bf16 v[32:35], v[208:211], v[176:179], v[32:35]
	v_mfma_f32_16x16x32_bf16 v[20:23], v[200:203], v[184:187], v[20:23]
	v_mfma_f32_16x16x32_bf16 v[16:19], v[208:211], v[184:187], v[16:19]
	v_mfma_f32_16x16x32_bf16 v[4:7], v[200:203], v[192:195], v[4:7]
	v_mfma_f32_16x16x32_bf16 v[0:3], v[208:211], v[192:195], v[0:3]
	v_mfma_f32_16x16x32_bf16 v[52:55], v[204:207], v[172:175], v[52:55]
	v_mfma_f32_16x16x32_bf16 v[48:51], v[212:215], v[172:175], v[48:51]
	v_mfma_f32_16x16x32_bf16 v[36:39], v[204:207], v[180:183], v[36:39]
	v_mfma_f32_16x16x32_bf16 v[32:35], v[212:215], v[180:183], v[32:35]
	v_mfma_f32_16x16x32_bf16 v[20:23], v[204:207], v[188:191], v[20:23]
	v_mfma_f32_16x16x32_bf16 v[16:19], v[212:215], v[188:191], v[16:19]
	v_mfma_f32_16x16x32_bf16 v[4:7], v[204:207], v[196:199], v[4:7]
	v_mfma_f32_16x16x32_bf16 v[0:3], v[212:215], v[196:199], v[0:3]
	s_setprio 0
	s_add_i32 s58, 0, 0x18000
	v_add_u32_e32 v164, s58, v145
	s_barrier
.Lg131_mid:
	ds_read_b128 v[152:155], v164
	ds_read_b128 v[156:159], v164 offset:1024
	ds_read_b128 v[160:163], v164 offset:2048
	ds_read_b128 v[164:167], v164 offset:3072
	s_add_u32 s28, s28, 0x40000
	s_addc_u32 s29, s29, 0
	s_mov_b32 m0, s43
	ds_read_b128 v[168:171], v150 offset:32768
	ds_read_b128 v[172:175], v150 offset:33792
	ds_read_b128 v[176:179], v150 offset:34816
	ds_read_b128 v[180:183], v150 offset:35840
	ds_read_b128 v[184:187], v150 offset:36864
	ds_read_b128 v[188:191], v150 offset:37888
	ds_read_b128 v[192:195], v150 offset:38912
	ds_read_b128 v[196:199], v150 offset:39936
	global_load_lds_dwordx4 v134, s[28:29]
	s_mov_b32 m0, s44
	s_nop 0
	global_load_lds_dwordx4 v130, s[28:29]
	s_waitcnt lgkmcnt(8)
	s_barrier
	s_waitcnt lgkmcnt(0)
	s_setprio 1
	s_waitcnt lgkmcnt(0)
	v_mfma_f32_16x16x32_bf16 v[124:127], v[152:155], v[168:171], v[124:127]
	v_mfma_f32_16x16x32_bf16 v[120:123], v[160:163], v[168:171], v[120:123]
	v_mfma_f32_16x16x32_bf16 v[108:111], v[152:155], v[176:179], v[108:111]
	v_mfma_f32_16x16x32_bf16 v[104:107], v[160:163], v[176:179], v[104:107]
	v_mfma_f32_16x16x32_bf16 v[92:95], v[152:155], v[184:187], v[92:95]
	v_mfma_f32_16x16x32_bf16 v[88:91], v[160:163], v[184:187], v[88:91]
	v_mfma_f32_16x16x32_bf16 v[76:79], v[152:155], v[192:195], v[76:79]
	v_mfma_f32_16x16x32_bf16 v[72:75], v[160:163], v[192:195], v[72:75]
	v_mfma_f32_16x16x32_bf16 v[124:127], v[156:159], v[172:175], v[124:127]
	v_mfma_f32_16x16x32_bf16 v[120:123], v[164:167], v[172:175], v[120:123]
	v_mfma_f32_16x16x32_bf16 v[108:111], v[156:159], v[180:183], v[108:111]
	v_mfma_f32_16x16x32_bf16 v[104:107], v[164:167], v[180:183], v[104:107]
	v_mfma_f32_16x16x32_bf16 v[92:95], v[156:159], v[188:191], v[92:95]
	v_mfma_f32_16x16x32_bf16 v[88:91], v[164:167], v[188:191], v[88:91]
	v_mfma_f32_16x16x32_bf16 v[76:79], v[156:159], v[196:199], v[76:79]
	v_mfma_f32_16x16x32_bf16 v[72:75], v[164:167], v[196:199], v[72:75]
	s_setprio 0
	s_barrier
	s_add_i32 s28, 0, 0x1c000
	s_add_i32 s29, s58, s38
	v_add_u32_e32 v212, s28, v145
	s_mov_b32 m0, s29
	ds_read_b128 v[200:203], v212
	ds_read_b128 v[204:207], v212 offset:1024
	ds_read_b128 v[208:211], v212 offset:2048
	ds_read_b128 v[212:215], v212 offset:3072
	global_load_lds_dwordx4 v132, s[80:81]
	s_add_i32 m0, s29, 0x2000
	s_nop 0
	global_load_lds_dwordx4 v128, s[80:81]
	s_waitcnt vmcnt(10)
	s_barrier
	s_waitcnt lgkmcnt(0)
	s_setprio 1
	s_waitcnt lgkmcnt(0)
	v_mfma_f32_16x16x32_bf16 v[116:119], v[200:203], v[168:171], v[116:119]
	v_mfma_f32_16x16x32_bf16 v[112:115], v[208:211], v[168:171], v[112:115]
	v_mfma_f32_16x16x32_bf16 v[100:103], v[200:203], v[176:179], v[100:103]
	v_mfma_f32_16x16x32_bf16 v[96:99], v[208:211], v[176:179], v[96:99]
	v_mfma_f32_16x16x32_bf16 v[84:87], v[200:203], v[184:187], v[84:87]
	v_mfma_f32_16x16x32_bf16 v[80:83], v[208:211], v[184:187], v[80:83]
	v_mfma_f32_16x16x32_bf16 v[68:71], v[200:203], v[192:195], v[68:71]
	v_mfma_f32_16x16x32_bf16 v[64:67], v[208:211], v[192:195], v[64:67]
	v_mfma_f32_16x16x32_bf16 v[116:119], v[204:207], v[172:175], v[116:119]
	v_mfma_f32_16x16x32_bf16 v[112:115], v[212:215], v[172:175], v[112:115]
	v_mfma_f32_16x16x32_bf16 v[100:103], v[204:207], v[180:183], v[100:103]
	v_mfma_f32_16x16x32_bf16 v[96:99], v[212:215], v[180:183], v[96:99]
	v_mfma_f32_16x16x32_bf16 v[84:87], v[204:207], v[188:191], v[84:87]
	v_mfma_f32_16x16x32_bf16 v[80:83], v[212:215], v[188:191], v[80:83]
	v_mfma_f32_16x16x32_bf16 v[68:71], v[204:207], v[196:199], v[68:71]
	v_mfma_f32_16x16x32_bf16 v[64:67], v[212:215], v[196:199], v[64:67]
	s_setprio 0
	s_mov_b32 m0, s45
	s_barrier
	ds_read_b128 v[168:171], v150 offset:49152
	ds_read_b128 v[172:175], v150 offset:50176
	ds_read_b128 v[176:179], v150 offset:51200
	ds_read_b128 v[180:183], v150 offset:52224
	ds_read_b128 v[184:187], v150 offset:53248
	ds_read_b128 v[188:191], v150 offset:54272
	ds_read_b128 v[192:195], v150 offset:55296
	ds_read_b128 v[196:199], v150 offset:56320
	global_load_lds_dwordx4 v134, s[82:83]
	s_mov_b32 m0, s46
	s_nop 0
	global_load_lds_dwordx4 v130, s[82:83]
	s_barrier
	s_waitcnt lgkmcnt(0)
	s_setprio 1
	s_waitcnt lgkmcnt(0)
	v_mfma_f32_16x16x32_bf16 v[60:63], v[152:155], v[168:171], v[60:63]
	v_mfma_f32_16x16x32_bf16 v[56:59], v[160:163], v[168:171], v[56:59]
	v_mfma_f32_16x16x32_bf16 v[44:47], v[152:155], v[176:179], v[44:47]
	v_mfma_f32_16x16x32_bf16 v[40:43], v[160:163], v[176:179], v[40:43]
	v_mfma_f32_16x16x32_bf16 v[28:31], v[152:155], v[184:187], v[28:31]
	v_mfma_f32_16x16x32_bf16 v[24:27], v[160:163], v[184:187], v[24:27]
	v_mfma_f32_16x16x32_bf16 v[12:15], v[152:155], v[192:195], v[12:15]
	v_mfma_f32_16x16x32_bf16 v[8:11], v[160:163], v[192:195], v[8:11]
	v_mfma_f32_16x16x32_bf16 v[60:63], v[156:159], v[172:175], v[60:63]
	v_mfma_f32_16x16x32_bf16 v[56:59], v[164:167], v[172:175], v[56:59]
	v_mfma_f32_16x16x32_bf16 v[44:47], v[156:159], v[180:183], v[44:47]
	v_mfma_f32_16x16x32_bf16 v[40:43], v[164:167], v[180:183], v[40:43]
	v_mfma_f32_16x16x32_bf16 v[28:31], v[156:159], v[188:191], v[28:31]
	v_mfma_f32_16x16x32_bf16 v[24:27], v[164:167], v[188:191], v[24:27]
	v_mfma_f32_16x16x32_bf16 v[12:15], v[156:159], v[196:199], v[12:15]
	v_mfma_f32_16x16x32_bf16 v[8:11], v[164:167], v[196:199], v[8:11]
	s_setprio 0
	s_barrier
	s_add_u32 s26, s26, 0x40080
	s_addc_u32 s27, s27, 0
	s_add_i32 s28, s28, s38
	s_mov_b32 m0, s28
	s_nop 0
	global_load_lds_dwordx4 v132, s[26:27]
	s_add_i32 m0, s28, 0x2000
	s_nop 0
	global_load_lds_dwordx4 v128, s[26:27]
	s_waitcnt vmcnt(8)
	s_barrier
	s_setprio 1
	v_mfma_f32_16x16x32_bf16 v[52:55], v[200:203], v[168:171], v[52:55]
	v_mfma_f32_16x16x32_bf16 v[48:51], v[208:211], v[168:171], v[48:51]
	v_mfma_f32_16x16x32_bf16 v[36:39], v[200:203], v[176:179], v[36:39]
	v_mfma_f32_16x16x32_bf16 v[32:35], v[208:211], v[176:179], v[32:35]
	v_mfma_f32_16x16x32_bf16 v[20:23], v[200:203], v[184:187], v[20:23]
	v_mfma_f32_16x16x32_bf16 v[16:19], v[208:211], v[184:187], v[16:19]
	v_mfma_f32_16x16x32_bf16 v[4:7], v[200:203], v[192:195], v[4:7]
	v_mfma_f32_16x16x32_bf16 v[0:3], v[208:211], v[192:195], v[0:3]
	v_mfma_f32_16x16x32_bf16 v[52:55], v[204:207], v[172:175], v[52:55]
	v_mfma_f32_16x16x32_bf16 v[48:51], v[212:215], v[172:175], v[48:51]
	v_mfma_f32_16x16x32_bf16 v[36:39], v[204:207], v[180:183], v[36:39]
	v_mfma_f32_16x16x32_bf16 v[32:35], v[212:215], v[180:183], v[32:35]
	v_mfma_f32_16x16x32_bf16 v[20:23], v[204:207], v[188:191], v[20:23]
	v_mfma_f32_16x16x32_bf16 v[16:19], v[212:215], v[188:191], v[16:19]
	v_mfma_f32_16x16x32_bf16 v[4:7], v[204:207], v[196:199], v[4:7]
	v_mfma_f32_16x16x32_bf16 v[0:3], v[212:215], v[196:199], v[0:3]
	s_setprio 0
	s_add_i32 s57, s57, 2
	s_add_u32 s20, s20, 0x100
	s_addc_u32 s21, s21, 0
	s_add_u32 s55, s55, 0x100
	s_addc_u32 s56, s56, 0
	s_cmp_gt_u32 s57, 13
	s_barrier
	s_cbranch_scc0 .LBB0_131
	s_cmpk_gt_u32 s37, 0xff
	s_cbranch_scc1 .Lg131_nox
	s_barrier

.Lg248_noy:
	ds_read_b128 v[144:147], v151
	ds_read_b128 v[156:159], v151 offset:1024
	ds_read_b128 v[160:163], v151 offset:2048
	ds_read_b128 v[164:167], v151 offset:3072
	s_add_u32 s26, s20, 0x100
	s_addc_u32 s27, s21, 0
	s_cmp_eq_u32 s59, 40
	s_cselect_b32 s31, s9, s27
	s_cselect_b32 s30, s8, s26
	s_cselect_b32 s29, s11, s58
	s_cselect_b32 s28, s10, s57
	s_add_i32 m0, s41, 0xc000
	ds_read_b128 v[168:171], v152
	ds_read_b128 v[172:175], v152 offset:1024
	ds_read_b128 v[176:179], v152 offset:2048
	ds_read_b128 v[180:183], v152 offset:3072
	ds_read_b128 v[184:187], v152 offset:4096
	ds_read_b128 v[188:191], v152 offset:5120
	ds_read_b128 v[192:195], v152 offset:6144
	ds_read_b128 v[196:199], v152 offset:7168
	global_load_lds_dwordx4 v136, s[20:21]
	s_add_i32 m0, s41, 0xe000
	s_nop 0
	global_load_lds_dwordx4 v138, s[20:21]
	s_waitcnt lgkmcnt(8)
	s_barrier
	s_waitcnt lgkmcnt(0)
	s_setprio 1
	s_waitcnt lgkmcnt(0)
	v_mfma_f32_16x16x32_bf16 v[124:127], v[144:147], v[168:171], 0
	v_mfma_f32_16x16x32_bf16 v[120:123], v[160:163], v[168:171], 0
	v_mfma_f32_16x16x32_bf16 v[108:111], v[144:147], v[176:179], 0
	v_mfma_f32_16x16x32_bf16 v[104:107], v[160:163], v[176:179], 0
	v_mfma_f32_16x16x32_bf16 v[92:95], v[144:147], v[184:187], 0
	v_mfma_f32_16x16x32_bf16 v[88:91], v[160:163], v[184:187], 0
	v_mfma_f32_16x16x32_bf16 v[76:79], v[144:147], v[192:195], 0
	v_mfma_f32_16x16x32_bf16 v[72:75], v[160:163], v[192:195], 0
	v_mfma_f32_16x16x32_bf16 v[124:127], v[156:159], v[172:175], v[124:127]
	v_mfma_f32_16x16x32_bf16 v[120:123], v[164:167], v[172:175], v[120:123]
	v_mfma_f32_16x16x32_bf16 v[108:111], v[156:159], v[180:183], v[108:111]
	v_mfma_f32_16x16x32_bf16 v[104:107], v[164:167], v[180:183], v[104:107]
	v_mfma_f32_16x16x32_bf16 v[92:95], v[156:159], v[188:191], v[92:95]
	v_mfma_f32_16x16x32_bf16 v[88:91], v[164:167], v[188:191], v[88:91]
	v_mfma_f32_16x16x32_bf16 v[76:79], v[156:159], v[196:199], v[76:79]
	v_mfma_f32_16x16x32_bf16 v[72:75], v[164:167], v[196:199], v[72:75]
	s_setprio 0
	s_barrier
	s_add_i32 s20, s51, s40
	s_add_u32 s80, s28, 0x80
	s_addc_u32 s81, s29, 0
	s_mov_b32 m0, s20
	ds_read_b128 v[200:203], v153
	ds_read_b128 v[204:207], v153 offset:1024
	ds_read_b128 v[208:211], v153 offset:2048
	ds_read_b128 v[212:215], v153 offset:3072
	global_load_lds_dwordx4 v130, s[28:29]
	s_add_i32 m0, s20, 0x2000
	s_nop 0
	global_load_lds_dwordx4 v134, s[28:29]
	s_waitcnt vmcnt(10)
	s_barrier
	s_waitcnt lgkmcnt(0)
	s_setprio 1
	s_waitcnt lgkmcnt(0)
	v_mfma_f32_16x16x32_bf16 v[116:119], v[200:203], v[168:171], 0
	v_mfma_f32_16x16x32_bf16 v[112:115], v[208:211], v[168:171], 0
	v_mfma_f32_16x16x32_bf16 v[100:103], v[200:203], v[176:179], 0
	v_mfma_f32_16x16x32_bf16 v[96:99], v[208:211], v[176:179], 0
	v_mfma_f32_16x16x32_bf16 v[84:87], v[200:203], v[184:187], 0
	v_mfma_f32_16x16x32_bf16 v[80:83], v[208:211], v[184:187], 0
	v_mfma_f32_16x16x32_bf16 v[68:71], v[200:203], v[192:195], 0
	v_mfma_f32_16x16x32_bf16 v[64:67], v[208:211], v[192:195], 0
	v_mfma_f32_16x16x32_bf16 v[116:119], v[204:207], v[172:175], v[116:119]
	v_mfma_f32_16x16x32_bf16 v[112:115], v[212:215], v[172:175], v[112:115]
	v_mfma_f32_16x16x32_bf16 v[100:103], v[204:207], v[180:183], v[100:103]
	v_mfma_f32_16x16x32_bf16 v[96:99], v[212:215], v[180:183], v[96:99]
	v_mfma_f32_16x16x32_bf16 v[84:87], v[204:207], v[188:191], v[84:87]
	v_mfma_f32_16x16x32_bf16 v[80:83], v[212:215], v[188:191], v[80:83]
	v_mfma_f32_16x16x32_bf16 v[68:71], v[204:207], v[196:199], v[68:71]
	v_mfma_f32_16x16x32_bf16 v[64:67], v[212:215], v[196:199], v[64:67]
	s_setprio 0
	s_mov_b32 m0, s41
	s_add_u32 s82, s30, 0x80
	s_addc_u32 s83, s31, 0
	s_barrier
	ds_read_b128 v[168:171], v152 offset:16384
	ds_read_b128 v[172:175], v152 offset:17408
	ds_read_b128 v[176:179], v152 offset:18432
	ds_read_b128 v[180:183], v152 offset:19456
	ds_read_b128 v[184:187], v152 offset:20480
	ds_read_b128 v[188:191], v152 offset:21504
	ds_read_b128 v[192:195], v152 offset:22528
	ds_read_b128 v[196:199], v152 offset:23552
	global_load_lds_dwordx4 v128, s[30:31]
	s_mov_b32 m0, s42
	s_nop 0
	global_load_lds_dwordx4 v132, s[30:31]
	s_barrier
	s_waitcnt lgkmcnt(0)
	s_setprio 1
	s_waitcnt lgkmcnt(0)
	v_mfma_f32_16x16x32_bf16 v[60:63], v[144:147], v[168:171], 0
	v_mfma_f32_16x16x32_bf16 v[56:59], v[160:163], v[168:171], 0
	v_mfma_f32_16x16x32_bf16 v[44:47], v[144:147], v[176:179], 0
	v_mfma_f32_16x16x32_bf16 v[40:43], v[160:163], v[176:179], 0
	v_mfma_f32_16x16x32_bf16 v[28:31], v[144:147], v[184:187], 0
	v_mfma_f32_16x16x32_bf16 v[24:27], v[160:163], v[184:187], 0
	v_mfma_f32_16x16x32_bf16 v[12:15], v[144:147], v[192:195], 0
	v_mfma_f32_16x16x32_bf16 v[8:11], v[160:163], v[192:195], 0
	v_mfma_f32_16x16x32_bf16 v[60:63], v[156:159], v[172:175], v[60:63]
	v_mfma_f32_16x16x32_bf16 v[56:59], v[164:167], v[172:175], v[56:59]
	v_mfma_f32_16x16x32_bf16 v[44:47], v[156:159], v[180:183], v[44:47]
	v_mfma_f32_16x16x32_bf16 v[40:43], v[164:167], v[180:183], v[40:43]
	v_mfma_f32_16x16x32_bf16 v[28:31], v[156:159], v[188:191], v[28:31]
	v_mfma_f32_16x16x32_bf16 v[24:27], v[164:167], v[188:191], v[24:27]
	v_mfma_f32_16x16x32_bf16 v[12:15], v[156:159], v[196:199], v[12:15]
	v_mfma_f32_16x16x32_bf16 v[8:11], v[164:167], v[196:199], v[8:11]
	s_setprio 0
	s_barrier
	s_add_u32 s20, s28, 0xb0000
	s_addc_u32 s21, s29, 0
	s_add_i32 s60, s52, s40
	s_mov_b32 m0, s60
	s_nop 0
	global_load_lds_dwordx4 v130, s[20:21]
	s_add_i32 m0, s60, 0x2000
	s_nop 0
	global_load_lds_dwordx4 v134, s[20:21]
	s_waitcnt vmcnt(8)
	s_barrier
	s_setprio 1
	v_mfma_f32_16x16x32_bf16 v[52:55], v[200:203], v[168:171], 0
	v_mfma_f32_16x16x32_bf16 v[48:51], v[208:211], v[168:171], 0
	v_mfma_f32_16x16x32_bf16 v[36:39], v[200:203], v[176:179], 0
	v_mfma_f32_16x16x32_bf16 v[32:35], v[208:211], v[176:179], 0
	v_mfma_f32_16x16x32_bf16 v[20:23], v[200:203], v[184:187], 0
	v_mfma_f32_16x16x32_bf16 v[16:19], v[208:211], v[184:187], 0
	v_mfma_f32_16x16x32_bf16 v[4:7], v[200:203], v[192:195], 0
	v_mfma_f32_16x16x32_bf16 v[0:3], v[208:211], v[192:195], 0
	v_mfma_f32_16x16x32_bf16 v[52:55], v[204:207], v[172:175], v[52:55]
	v_mfma_f32_16x16x32_bf16 v[48:51], v[212:215], v[172:175], v[48:51]
	v_mfma_f32_16x16x32_bf16 v[36:39], v[204:207], v[180:183], v[36:39]
	v_mfma_f32_16x16x32_bf16 v[32:35], v[212:215], v[180:183], v[32:35]
	v_mfma_f32_16x16x32_bf16 v[20:23], v[204:207], v[188:191], v[20:23]
	v_mfma_f32_16x16x32_bf16 v[16:19], v[212:215], v[188:191], v[16:19]
	v_mfma_f32_16x16x32_bf16 v[4:7], v[204:207], v[196:199], v[4:7]
	v_mfma_f32_16x16x32_bf16 v[0:3], v[212:215], v[196:199], v[0:3]
	s_setprio 0
	s_add_i32 s60, 0, 0x18000
	v_add_u32_e32 v155, s60, v149
	s_barrier
	s_branch .Lg248_mid
.LBB0_248:
	ds_read_b128 v[144:147], v151
	ds_read_b128 v[156:159], v151 offset:1024
	ds_read_b128 v[160:163], v151 offset:2048
	ds_read_b128 v[164:167], v151 offset:3072
	s_add_u32 s26, s20, 0x100
	s_addc_u32 s27, s21, 0
	s_cmp_eq_u32 s59, 40
	s_cselect_b32 s31, s9, s27
	s_cselect_b32 s30, s8, s26
	s_cselect_b32 s29, s11, s58
	s_cselect_b32 s28, s10, s57
	s_add_i32 m0, s41, 0xc000
	ds_read_b128 v[168:171], v152
	ds_read_b128 v[172:175], v152 offset:1024
	ds_read_b128 v[176:179], v152 offset:2048
	ds_read_b128 v[180:183], v152 offset:3072
	ds_read_b128 v[184:187], v152 offset:4096
	ds_read_b128 v[188:191], v152 offset:5120
	ds_read_b128 v[192:195], v152 offset:6144
	ds_read_b128 v[196:199], v152 offset:7168
	global_load_lds_dwordx4 v136, s[20:21]
	s_add_i32 m0, s41, 0xe000
	s_nop 0
	global_load_lds_dwordx4 v138, s[20:21]
	s_waitcnt lgkmcnt(8)
	s_barrier
	s_waitcnt lgkmcnt(0)
	s_setprio 1
	s_waitcnt lgkmcnt(0)
	v_mfma_f32_16x16x32_bf16 v[124:127], v[144:147], v[168:171], v[124:127]
	v_mfma_f32_16x16x32_bf16 v[120:123], v[160:163], v[168:171], v[120:123]
	v_mfma_f32_16x16x32_bf16 v[108:111], v[144:147], v[176:179], v[108:111]
	v_mfma_f32_16x16x32_bf16 v[104:107], v[160:163], v[176:179], v[104:107]
	v_mfma_f32_16x16x32_bf16 v[92:95], v[144:147], v[184:187], v[92:95]
	v_mfma_f32_16x16x32_bf16 v[88:91], v[160:163], v[184:187], v[88:91]
	v_mfma_f32_16x16x32_bf16 v[76:79], v[144:147], v[192:195], v[76:79]
	v_mfma_f32_16x16x32_bf16 v[72:75], v[160:163], v[192:195], v[72:75]
	v_mfma_f32_16x16x32_bf16 v[124:127], v[156:159], v[172:175], v[124:127]
	v_mfma_f32_16x16x32_bf16 v[120:123], v[164:167], v[172:175], v[120:123]
	v_mfma_f32_16x16x32_bf16 v[108:111], v[156:159], v[180:183], v[108:111]
	v_mfma_f32_16x16x32_bf16 v[104:107], v[164:167], v[180:183], v[104:107]
	v_mfma_f32_16x16x32_bf16 v[92:95], v[156:159], v[188:191], v[92:95]
	v_mfma_f32_16x16x32_bf16 v[88:91], v[164:167], v[188:191], v[88:91]
	v_mfma_f32_16x16x32_bf16 v[76:79], v[156:159], v[196:199], v[76:79]
	v_mfma_f32_16x16x32_bf16 v[72:75], v[164:167], v[196:199], v[72:75]
	s_setprio 0
	s_barrier
	s_add_i32 s20, s51, s40
	s_add_u32 s80, s28, 0x80
	s_addc_u32 s81, s29, 0
	s_mov_b32 m0, s20
	ds_read_b128 v[200:203], v153
	ds_read_b128 v[204:207], v153 offset:1024
	ds_read_b128 v[208:211], v153 offset:2048
	ds_read_b128 v[212:215], v153 offset:3072
	global_load_lds_dwordx4 v130, s[28:29]
	s_add_i32 m0, s20, 0x2000
	s_nop 0
	global_load_lds_dwordx4 v134, s[28:29]
	s_waitcnt vmcnt(10)
	s_barrier
	s_waitcnt lgkmcnt(0)
	s_setprio 1
	s_waitcnt lgkmcnt(0)
	v_mfma_f32_16x16x32_bf16 v[116:119], v[200:203], v[168:171], v[116:119]
	v_mfma_f32_16x16x32_bf16 v[112:115], v[208:211], v[168:171], v[112:115]
	v_mfma_f32_16x16x32_bf16 v[100:103], v[200:203], v[176:179], v[100:103]
	v_mfma_f32_16x16x32_bf16 v[96:99], v[208:211], v[176:179], v[96:99]
	v_mfma_f32_16x16x32_bf16 v[84:87], v[200:203], v[184:187], v[84:87]
	v_mfma_f32_16x16x32_bf16 v[80:83], v[208:211], v[184:187], v[80:83]
	v_mfma_f32_16x16x32_bf16 v[68:71], v[200:203], v[192:195], v[68:71]
	v_mfma_f32_16x16x32_bf16 v[64:67], v[208:211], v[192:195], v[64:67]
	v_mfma_f32_16x16x32_bf16 v[116:119], v[204:207], v[172:175], v[116:119]
	v_mfma_f32_16x16x32_bf16 v[112:115], v[212:215], v[172:175], v[112:115]
	v_mfma_f32_16x16x32_bf16 v[100:103], v[204:207], v[180:183], v[100:103]
	v_mfma_f32_16x16x32_bf16 v[96:99], v[212:215], v[180:183], v[96:99]
	v_mfma_f32_16x16x32_bf16 v[84:87], v[204:207], v[188:191], v[84:87]
	v_mfma_f32_16x16x32_bf16 v[80:83], v[212:215], v[188:191], v[80:83]
	v_mfma_f32_16x16x32_bf16 v[68:71], v[204:207], v[196:199], v[68:71]
	v_mfma_f32_16x16x32_bf16 v[64:67], v[212:215], v[196:199], v[64:67]
	s_setprio 0
	s_mov_b32 m0, s41
	s_add_u32 s82, s30, 0x80
	s_addc_u32 s83, s31, 0
	s_barrier
	ds_read_b128 v[168:171], v152 offset:16384
	ds_read_b128 v[172:175], v152 offset:17408
	ds_read_b128 v[176:179], v152 offset:18432
	ds_read_b128 v[180:183], v152 offset:19456
	ds_read_b128 v[184:187], v152 offset:20480
	ds_read_b128 v[188:191], v152 offset:21504
	ds_read_b128 v[192:195], v152 offset:22528
	ds_read_b128 v[196:199], v152 offset:23552
	global_load_lds_dwordx4 v128, s[30:31]
	s_mov_b32 m0, s42
	s_nop 0
	global_load_lds_dwordx4 v132, s[30:31]
	s_barrier
	s_waitcnt lgkmcnt(0)
	s_setprio 1
	s_waitcnt lgkmcnt(0)
	v_mfma_f32_16x16x32_bf16 v[60:63], v[144:147], v[168:171], v[60:63]
	v_mfma_f32_16x16x32_bf16 v[56:59], v[160:163], v[168:171], v[56:59]
	v_mfma_f32_16x16x32_bf16 v[44:47], v[144:147], v[176:179], v[44:47]
	v_mfma_f32_16x16x32_bf16 v[40:43], v[160:163], v[176:179], v[40:43]
	v_mfma_f32_16x16x32_bf16 v[28:31], v[144:147], v[184:187], v[28:31]
	v_mfma_f32_16x16x32_bf16 v[24:27], v[160:163], v[184:187], v[24:27]
	v_mfma_f32_16x16x32_bf16 v[12:15], v[144:147], v[192:195], v[12:15]
	v_mfma_f32_16x16x32_bf16 v[8:11], v[160:163], v[192:195], v[8:11]
	v_mfma_f32_16x16x32_bf16 v[60:63], v[156:159], v[172:175], v[60:63]
	v_mfma_f32_16x16x32_bf16 v[56:59], v[164:167], v[172:175], v[56:59]
	v_mfma_f32_16x16x32_bf16 v[44:47], v[156:159], v[180:183], v[44:47]
	v_mfma_f32_16x16x32_bf16 v[40:43], v[164:167], v[180:183], v[40:43]
	v_mfma_f32_16x16x32_bf16 v[28:31], v[156:159], v[188:191], v[28:31]
	v_mfma_f32_16x16x32_bf16 v[24:27], v[164:167], v[188:191], v[24:27]
	v_mfma_f32_16x16x32_bf16 v[12:15], v[156:159], v[196:199], v[12:15]
	v_mfma_f32_16x16x32_bf16 v[8:11], v[164:167], v[196:199], v[8:11]
	s_setprio 0
	s_barrier
	s_add_u32 s20, s28, 0xb0000
	s_addc_u32 s21, s29, 0
	s_add_i32 s60, s52, s40
	s_mov_b32 m0, s60
	s_nop 0
	global_load_lds_dwordx4 v130, s[20:21]
	s_add_i32 m0, s60, 0x2000
	s_nop 0
	global_load_lds_dwordx4 v134, s[20:21]
	s_waitcnt vmcnt(8)
	s_barrier
	s_setprio 1
	v_mfma_f32_16x16x32_bf16 v[52:55], v[200:203], v[168:171], v[52:55]
	v_mfma_f32_16x16x32_bf16 v[48:51], v[208:211], v[168:171], v[48:51]
	v_mfma_f32_16x16x32_bf16 v[36:39], v[200:203], v[176:179], v[36:39]
	v_mfma_f32_16x16x32_bf16 v[32:35], v[208:211], v[176:179], v[32:35]
	v_mfma_f32_16x16x32_bf16 v[20:23], v[200:203], v[184:187], v[20:23]
	v_mfma_f32_16x16x32_bf16 v[16:19], v[208:211], v[184:187], v[16:19]
	v_mfma_f32_16x16x32_bf16 v[4:7], v[200:203], v[192:195], v[4:7]
	v_mfma_f32_16x16x32_bf16 v[0:3], v[208:211], v[192:195], v[0:3]
	v_mfma_f32_16x16x32_bf16 v[52:55], v[204:207], v[172:175], v[52:55]
	v_mfma_f32_16x16x32_bf16 v[48:51], v[212:215], v[172:175], v[48:51]
	v_mfma_f32_16x16x32_bf16 v[36:39], v[204:207], v[180:183], v[36:39]
	v_mfma_f32_16x16x32_bf16 v[32:35], v[212:215], v[180:183], v[32:35]
	v_mfma_f32_16x16x32_bf16 v[20:23], v[204:207], v[188:191], v[20:23]
	v_mfma_f32_16x16x32_bf16 v[16:19], v[212:215], v[188:191], v[16:19]
	v_mfma_f32_16x16x32_bf16 v[4:7], v[204:207], v[196:199], v[4:7]
	v_mfma_f32_16x16x32_bf16 v[0:3], v[212:215], v[196:199], v[0:3]
	s_setprio 0
	s_add_i32 s60, 0, 0x18000
	v_add_u32_e32 v155, s60, v149
	s_barrier
.Lg248_mid:
	ds_read_b128 v[144:147], v155
	ds_read_b128 v[156:159], v155 offset:1024
	ds_read_b128 v[160:163], v155 offset:2048
	ds_read_b128 v[164:167], v155 offset:3072
	s_add_u32 s20, s30, 0xb0000
	s_addc_u32 s21, s31, 0
	s_mov_b32 m0, s43
	ds_read_b128 v[168:171], v152 offset:32768
	ds_read_b128 v[172:175], v152 offset:33792
	ds_read_b128 v[176:179], v152 offset:34816
	ds_read_b128 v[180:183], v152 offset:35840
	ds_read_b128 v[184:187], v152 offset:36864
	ds_read_b128 v[188:191], v152 offset:37888
	ds_read_b128 v[192:195], v152 offset:38912
	ds_read_b128 v[196:199], v152 offset:39936
	global_load_lds_dwordx4 v128, s[20:21]
	s_mov_b32 m0, s44
	s_nop 0
	global_load_lds_dwordx4 v132, s[20:21]
	s_waitcnt lgkmcnt(8)
	s_barrier
	s_waitcnt lgkmcnt(0)
	s_setprio 1
	s_waitcnt lgkmcnt(0)
	v_mfma_f32_16x16x32_bf16 v[124:127], v[144:147], v[168:171], v[124:127]
	v_mfma_f32_16x16x32_bf16 v[120:123], v[160:163], v[168:171], v[120:123]
	v_mfma_f32_16x16x32_bf16 v[108:111], v[144:147], v[176:179], v[108:111]
	v_mfma_f32_16x16x32_bf16 v[104:107], v[160:163], v[176:179], v[104:107]
	v_mfma_f32_16x16x32_bf16 v[92:95], v[144:147], v[184:187], v[92:95]
	v_mfma_f32_16x16x32_bf16 v[88:91], v[160:163], v[184:187], v[88:91]
	v_mfma_f32_16x16x32_bf16 v[76:79], v[144:147], v[192:195], v[76:79]
	v_mfma_f32_16x16x32_bf16 v[72:75], v[160:163], v[192:195], v[72:75]
	v_mfma_f32_16x16x32_bf16 v[124:127], v[156:159], v[172:175], v[124:127]
	v_mfma_f32_16x16x32_bf16 v[120:123], v[164:167], v[172:175], v[120:123]
	v_mfma_f32_16x16x32_bf16 v[108:111], v[156:159], v[180:183], v[108:111]
	v_mfma_f32_16x16x32_bf16 v[104:107], v[164:167], v[180:183], v[104:107]
	v_mfma_f32_16x16x32_bf16 v[92:95], v[156:159], v[188:191], v[92:95]
	v_mfma_f32_16x16x32_bf16 v[88:91], v[164:167], v[188:191], v[88:91]
	v_mfma_f32_16x16x32_bf16 v[76:79], v[156:159], v[196:199], v[76:79]
	v_mfma_f32_16x16x32_bf16 v[72:75], v[164:167], v[196:199], v[72:75]
	s_setprio 0
	s_barrier
	s_add_i32 s30, 0, 0x1c000
	s_add_i32 s20, s60, s40
	v_add_u32_e32 v155, s30, v149
	s_mov_b32 m0, s20
	ds_read_b128 v[200:203], v155
	ds_read_b128 v[204:207], v155 offset:1024
	ds_read_b128 v[208:211], v155 offset:2048
	ds_read_b128 v[212:215], v155 offset:3072
	global_load_lds_dwordx4 v130, s[80:81]
	s_add_i32 m0, s20, 0x2000
	s_nop 0
	global_load_lds_dwordx4 v134, s[80:81]
	s_waitcnt vmcnt(10)
	s_barrier
	s_waitcnt lgkmcnt(0)
	s_setprio 1
	s_waitcnt lgkmcnt(0)
	v_mfma_f32_16x16x32_bf16 v[116:119], v[200:203], v[168:171], v[116:119]
	v_mfma_f32_16x16x32_bf16 v[112:115], v[208:211], v[168:171], v[112:115]
	v_mfma_f32_16x16x32_bf16 v[100:103], v[200:203], v[176:179], v[100:103]
	v_mfma_f32_16x16x32_bf16 v[96:99], v[208:211], v[176:179], v[96:99]
	v_mfma_f32_16x16x32_bf16 v[84:87], v[200:203], v[184:187], v[84:87]
	v_mfma_f32_16x16x32_bf16 v[80:83], v[208:211], v[184:187], v[80:83]
	v_mfma_f32_16x16x32_bf16 v[68:71], v[200:203], v[192:195], v[68:71]
	v_mfma_f32_16x16x32_bf16 v[64:67], v[208:211], v[192:195], v[64:67]
	v_mfma_f32_16x16x32_bf16 v[116:119], v[204:207], v[172:175], v[116:119]
	v_mfma_f32_16x16x32_bf16 v[112:115], v[212:215], v[172:175], v[112:115]
	v_mfma_f32_16x16x32_bf16 v[100:103], v[204:207], v[180:183], v[100:103]
	v_mfma_f32_16x16x32_bf16 v[96:99], v[212:215], v[180:183], v[96:99]
	v_mfma_f32_16x16x32_bf16 v[84:87], v[204:207], v[188:191], v[84:87]
	v_mfma_f32_16x16x32_bf16 v[80:83], v[212:215], v[188:191], v[80:83]
	v_mfma_f32_16x16x32_bf16 v[68:71], v[204:207], v[196:199], v[68:71]
	v_mfma_f32_16x16x32_bf16 v[64:67], v[212:215], v[196:199], v[64:67]
	s_setprio 0
	s_mov_b32 m0, s46
	s_barrier
	ds_read_b128 v[168:171], v152 offset:49152
	ds_read_b128 v[172:175], v152 offset:50176
	ds_read_b128 v[176:179], v152 offset:51200
	ds_read_b128 v[180:183], v152 offset:52224
	ds_read_b128 v[184:187], v152 offset:53248
	ds_read_b128 v[188:191], v152 offset:54272
	ds_read_b128 v[192:195], v152 offset:55296
	ds_read_b128 v[196:199], v152 offset:56320
	global_load_lds_dwordx4 v128, s[82:83]
	s_mov_b32 m0, s47
	s_nop 0
	global_load_lds_dwordx4 v132, s[82:83]
	s_barrier
	s_waitcnt lgkmcnt(0)
	s_setprio 1
	s_waitcnt lgkmcnt(0)
	v_mfma_f32_16x16x32_bf16 v[60:63], v[144:147], v[168:171], v[60:63]
	v_mfma_f32_16x16x32_bf16 v[56:59], v[160:163], v[168:171], v[56:59]
	v_mfma_f32_16x16x32_bf16 v[44:47], v[144:147], v[176:179], v[44:47]
	v_mfma_f32_16x16x32_bf16 v[40:43], v[160:163], v[176:179], v[40:43]
	v_mfma_f32_16x16x32_bf16 v[28:31], v[144:147], v[184:187], v[28:31]
	v_mfma_f32_16x16x32_bf16 v[24:27], v[160:163], v[184:187], v[24:27]
	v_mfma_f32_16x16x32_bf16 v[12:15], v[144:147], v[192:195], v[12:15]
	v_mfma_f32_16x16x32_bf16 v[8:11], v[160:163], v[192:195], v[8:11]
	v_mfma_f32_16x16x32_bf16 v[60:63], v[156:159], v[172:175], v[60:63]
	v_mfma_f32_16x16x32_bf16 v[56:59], v[164:167], v[172:175], v[56:59]
	v_mfma_f32_16x16x32_bf16 v[44:47], v[156:159], v[180:183], v[44:47]
	v_mfma_f32_16x16x32_bf16 v[40:43], v[164:167], v[180:183], v[40:43]
	v_mfma_f32_16x16x32_bf16 v[28:31], v[156:159], v[188:191], v[28:31]
	v_mfma_f32_16x16x32_bf16 v[24:27], v[164:167], v[188:191], v[24:27]
	v_mfma_f32_16x16x32_bf16 v[12:15], v[156:159], v[196:199], v[12:15]
	v_mfma_f32_16x16x32_bf16 v[8:11], v[164:167], v[196:199], v[8:11]
	s_setprio 0
	s_barrier
	s_add_u32 s20, s28, 0xb0080
	s_addc_u32 s21, s29, 0
	s_add_i32 s28, s30, s40
	s_mov_b32 m0, s28
	s_nop 0
	global_load_lds_dwordx4 v130, s[20:21]
	s_add_i32 m0, s28, 0x2000
	s_nop 0
	global_load_lds_dwordx4 v134, s[20:21]
	s_waitcnt vmcnt(8)
	s_barrier
	s_setprio 1
	v_mfma_f32_16x16x32_bf16 v[52:55], v[200:203], v[168:171], v[52:55]
	v_mfma_f32_16x16x32_bf16 v[48:51], v[208:211], v[168:171], v[48:51]
	v_mfma_f32_16x16x32_bf16 v[36:39], v[200:203], v[176:179], v[36:39]
	v_mfma_f32_16x16x32_bf16 v[32:35], v[208:211], v[176:179], v[32:35]
	v_mfma_f32_16x16x32_bf16 v[20:23], v[200:203], v[184:187], v[20:23]
	v_mfma_f32_16x16x32_bf16 v[16:19], v[208:211], v[184:187], v[16:19]
	v_mfma_f32_16x16x32_bf16 v[4:7], v[200:203], v[192:195], v[4:7]
	v_mfma_f32_16x16x32_bf16 v[0:3], v[208:211], v[192:195], v[0:3]
	v_mfma_f32_16x16x32_bf16 v[52:55], v[204:207], v[172:175], v[52:55]
	v_mfma_f32_16x16x32_bf16 v[48:51], v[212:215], v[172:175], v[48:51]
	v_mfma_f32_16x16x32_bf16 v[36:39], v[204:207], v[180:183], v[36:39]
	v_mfma_f32_16x16x32_bf16 v[32:35], v[212:215], v[180:183], v[32:35]
	v_mfma_f32_16x16x32_bf16 v[20:23], v[204:207], v[188:191], v[20:23]
	v_mfma_f32_16x16x32_bf16 v[16:19], v[212:215], v[188:191], v[16:19]
	v_mfma_f32_16x16x32_bf16 v[4:7], v[204:207], v[196:199], v[4:7]
	v_mfma_f32_16x16x32_bf16 v[0:3], v[212:215], v[196:199], v[0:3]
	s_setprio 0
	s_add_i32 s59, s59, 2
	s_add_u32 s57, s57, 0x100
	s_addc_u32 s58, s58, 0
	s_cmp_gt_u32 s59, 41
	s_mov_b64 s[20:21], s[26:27]
	s_barrier
	s_cbranch_scc0 .LBB0_248
	v_lshl_add_u32 v146, s56, 8, v148
	v_ashrrev_i32_e32 v147, 31, v146
	v_lshl_or_b32 v144, s12, 8, v150
	v_lshlrev_b64 v[156:157], 11, v[146:147]
	v_ashrrev_i32_e32 v145, 31, v144
	v_lshl_add_u64 v[156:157], s[14:15], 0, v[156:157]
	v_lshl_add_u64 v[166:167], v[144:145], 1, v[156:157]
	global_load_dwordx4 v[158:161], v[166:167], off
	global_load_dwordx4 v[162:165], v[166:167], off offset:256
	s_mov_b64 s[84:85], 0x8000
	s_mov_b64 s[86:87], 0x28000
	v_lshl_add_u64 v[232:233], v[166:167], 0, s[84:85]
	global_load_dwordx4 v[176:179], v[232:233], off
	global_load_dwordx4 v[180:183], v[232:233], off offset:256
	v_lshl_add_u64 v[232:233], v[232:233], 0, s[84:85]
	global_load_dwordx4 v[184:187], v[232:233], off
	global_load_dwordx4 v[188:191], v[232:233], off offset:256
	v_lshl_add_u64 v[232:233], v[232:233], 0, s[84:85]
	global_load_dwordx4 v[192:195], v[232:233], off
	global_load_dwordx4 v[196:199], v[232:233], off offset:256
	v_lshl_add_u64 v[232:233], v[232:233], 0, s[86:87]
	global_load_dwordx4 v[200:203], v[232:233], off
	global_load_dwordx4 v[204:207], v[232:233], off offset:256
	v_lshl_add_u64 v[232:233], v[232:233], 0, s[84:85]
	global_load_dwordx4 v[208:211], v[232:233], off
	global_load_dwordx4 v[212:215], v[232:233], off offset:256
	v_lshl_add_u64 v[232:233], v[232:233], 0, s[84:85]
	global_load_dwordx4 v[216:219], v[232:233], off
	global_load_dwordx4 v[220:223], v[232:233], off offset:256
	v_lshl_add_u64 v[232:233], v[232:233], 0, s[84:85]
	global_load_dwordx4 v[224:227], v[232:233], off
	global_load_dwordx4 v[228:231], v[232:233], off offset:256
	s_cmpk_gt_u32 s35, 0xff
	s_cbranch_scc1 .Lg248_nox
	s_barrier

.Lg359_noy:
	ds_read_b128 v[128:131], v181
	ds_read_b128 v[132:135], v181 offset:1024
	ds_read_b128 v[136:139], v181 offset:2048
	ds_read_b128 v[166:169], v181 offset:3072
	s_add_u32 s38, s8, 0xfffc0080
	s_addc_u32 s39, s9, -1
	s_cmp_eq_u32 s75, 12
	s_cselect_b32 s41, s21, s39
	s_cselect_b32 s40, s71, s38
	s_cselect_b32 s39, s19, s74
	s_cselect_b32 s38, s72, s73
	s_add_i32 m0, s37, 0xc000
	ds_read_b128 v[170:173], v182
	ds_read_b128 v[174:177], v182 offset:1024
	ds_read_b128 v[192:195], v182 offset:2048
	ds_read_b128 v[196:199], v182 offset:3072
	ds_read_b128 v[200:203], v182 offset:4096
	ds_read_b128 v[204:207], v182 offset:5120
	ds_read_b128 v[208:211], v182 offset:6144
	ds_read_b128 v[212:215], v182 offset:7168
	global_load_lds_dwordx4 v158, s[8:9]
	s_add_i32 m0, s37, 0xe000
	s_nop 0
	global_load_lds_dwordx4 v160, s[8:9]
	s_waitcnt lgkmcnt(8)
	s_barrier
	s_waitcnt lgkmcnt(0)
	s_setprio 1
	s_waitcnt lgkmcnt(0)
	v_mfma_f32_16x16x32_bf16 v[124:127], v[128:131], v[170:173], 0
	v_mfma_f32_16x16x32_bf16 v[116:119], v[136:139], v[170:173], 0
	v_mfma_f32_16x16x32_bf16 v[108:111], v[128:131], v[192:195], 0
	v_mfma_f32_16x16x32_bf16 v[100:103], v[136:139], v[192:195], 0
	v_mfma_f32_16x16x32_bf16 v[92:95], v[128:131], v[200:203], 0
	v_mfma_f32_16x16x32_bf16 v[84:87], v[136:139], v[200:203], 0
	v_mfma_f32_16x16x32_bf16 v[76:79], v[128:131], v[208:211], 0
	v_mfma_f32_16x16x32_bf16 v[68:71], v[136:139], v[208:211], 0
	v_mfma_f32_16x16x32_bf16 v[124:127], v[132:135], v[174:177], v[124:127]
	v_mfma_f32_16x16x32_bf16 v[116:119], v[166:169], v[174:177], v[116:119]
	v_mfma_f32_16x16x32_bf16 v[108:111], v[132:135], v[196:199], v[108:111]
	v_mfma_f32_16x16x32_bf16 v[100:103], v[166:169], v[196:199], v[100:103]
	v_mfma_f32_16x16x32_bf16 v[92:95], v[132:135], v[204:207], v[92:95]
	v_mfma_f32_16x16x32_bf16 v[84:87], v[166:169], v[204:207], v[84:87]
	v_mfma_f32_16x16x32_bf16 v[76:79], v[132:135], v[212:215], v[76:79]
	v_mfma_f32_16x16x32_bf16 v[68:71], v[166:169], v[212:215], v[68:71]
	s_setprio 0
	s_barrier
	s_add_i32 s76, s63, s46
	s_add_u32 s80, s38, 0x80
	s_addc_u32 s81, s39, 0
	s_mov_b32 m0, s76
	ds_read_b128 v[216:219], v183
	ds_read_b128 v[220:223], v183 offset:1024
	ds_read_b128 v[224:227], v183 offset:2048
	ds_read_b128 v[228:231], v183 offset:3072
	global_load_lds_dwordx4 v144, s[38:39]
	s_add_i32 m0, s76, 0x2000
	s_nop 0
	global_load_lds_dwordx4 v148, s[38:39]
	s_waitcnt vmcnt(10)
	s_barrier
	s_waitcnt lgkmcnt(0)
	s_setprio 1
	s_waitcnt lgkmcnt(0)
	v_mfma_f32_16x16x32_bf16 v[120:123], v[216:219], v[170:173], 0
	v_mfma_f32_16x16x32_bf16 v[112:115], v[224:227], v[170:173], 0
	v_mfma_f32_16x16x32_bf16 v[104:107], v[216:219], v[192:195], 0
	v_mfma_f32_16x16x32_bf16 v[96:99], v[224:227], v[192:195], 0
	v_mfma_f32_16x16x32_bf16 v[88:91], v[216:219], v[200:203], 0
	v_mfma_f32_16x16x32_bf16 v[80:83], v[224:227], v[200:203], 0
	v_mfma_f32_16x16x32_bf16 v[72:75], v[216:219], v[208:211], 0
	v_mfma_f32_16x16x32_bf16 v[64:67], v[224:227], v[208:211], 0
	v_mfma_f32_16x16x32_bf16 v[120:123], v[220:223], v[174:177], v[120:123]
	v_mfma_f32_16x16x32_bf16 v[112:115], v[228:231], v[174:177], v[112:115]
	v_mfma_f32_16x16x32_bf16 v[104:107], v[220:223], v[196:199], v[104:107]
	v_mfma_f32_16x16x32_bf16 v[96:99], v[228:231], v[196:199], v[96:99]
	v_mfma_f32_16x16x32_bf16 v[88:91], v[220:223], v[204:207], v[88:91]
	v_mfma_f32_16x16x32_bf16 v[80:83], v[228:231], v[204:207], v[80:83]
	v_mfma_f32_16x16x32_bf16 v[72:75], v[220:223], v[212:215], v[72:75]
	v_mfma_f32_16x16x32_bf16 v[64:67], v[228:231], v[212:215], v[64:67]
	s_setprio 0
	s_mov_b32 m0, s37
	s_add_u32 s82, s40, 0x80
	s_addc_u32 s83, s41, 0
	s_barrier
	ds_read_b128 v[170:173], v182 offset:16384
	ds_read_b128 v[174:177], v182 offset:17408
	ds_read_b128 v[192:195], v182 offset:18432
	ds_read_b128 v[196:199], v182 offset:19456
	ds_read_b128 v[200:203], v182 offset:20480
	ds_read_b128 v[204:207], v182 offset:21504
	ds_read_b128 v[208:211], v182 offset:22528
	ds_read_b128 v[212:215], v182 offset:23552
	global_load_lds_dwordx4 v142, s[40:41]
	s_mov_b32 m0, s51
	s_nop 0
	global_load_lds_dwordx4 v146, s[40:41]
	s_barrier
	s_waitcnt lgkmcnt(0)
	s_setprio 1
	s_waitcnt lgkmcnt(0)
	v_mfma_f32_16x16x32_bf16 v[60:63], v[128:131], v[170:173], 0
	v_mfma_f32_16x16x32_bf16 v[52:55], v[136:139], v[170:173], 0
	v_mfma_f32_16x16x32_bf16 v[44:47], v[128:131], v[192:195], 0
	v_mfma_f32_16x16x32_bf16 v[36:39], v[136:139], v[192:195], 0
	v_mfma_f32_16x16x32_bf16 v[28:31], v[128:131], v[200:203], 0
	v_mfma_f32_16x16x32_bf16 v[20:23], v[136:139], v[200:203], 0
	v_mfma_f32_16x16x32_bf16 v[12:15], v[128:131], v[208:211], 0
	v_mfma_f32_16x16x32_bf16 v[4:7], v[136:139], v[208:211], 0
	v_mfma_f32_16x16x32_bf16 v[60:63], v[132:135], v[174:177], v[60:63]
	v_mfma_f32_16x16x32_bf16 v[52:55], v[166:169], v[174:177], v[52:55]
	v_mfma_f32_16x16x32_bf16 v[44:47], v[132:135], v[196:199], v[44:47]
	v_mfma_f32_16x16x32_bf16 v[36:39], v[166:169], v[196:199], v[36:39]
	v_mfma_f32_16x16x32_bf16 v[28:31], v[132:135], v[204:207], v[28:31]
	v_mfma_f32_16x16x32_bf16 v[20:23], v[166:169], v[204:207], v[20:23]
	v_mfma_f32_16x16x32_bf16 v[12:15], v[132:135], v[212:215], v[12:15]
	v_mfma_f32_16x16x32_bf16 v[4:7], v[166:169], v[212:215], v[4:7]
	s_setprio 0
	s_barrier
	s_add_u32 s76, s38, 0x40000
	s_addc_u32 s77, s39, 0
	s_add_i32 s78, s64, s46
	s_mov_b32 m0, s78
	s_nop 0
	global_load_lds_dwordx4 v144, s[76:77]
	s_add_i32 m0, s78, 0x2000
	s_nop 0
	global_load_lds_dwordx4 v148, s[76:77]
	s_waitcnt vmcnt(8)
	s_barrier
	s_setprio 1
	v_mfma_f32_16x16x32_bf16 v[56:59], v[216:219], v[170:173], 0
	v_mfma_f32_16x16x32_bf16 v[48:51], v[224:227], v[170:173], 0
	v_mfma_f32_16x16x32_bf16 v[40:43], v[216:219], v[192:195], 0
	v_mfma_f32_16x16x32_bf16 v[32:35], v[224:227], v[192:195], 0
	v_mfma_f32_16x16x32_bf16 v[24:27], v[216:219], v[200:203], 0
	v_mfma_f32_16x16x32_bf16 v[16:19], v[224:227], v[200:203], 0
	v_mfma_f32_16x16x32_bf16 v[8:11], v[216:219], v[208:211], 0
	v_mfma_f32_16x16x32_bf16 v[0:3], v[224:227], v[208:211], 0
	v_mfma_f32_16x16x32_bf16 v[56:59], v[220:223], v[174:177], v[56:59]
	v_mfma_f32_16x16x32_bf16 v[48:51], v[228:231], v[174:177], v[48:51]
	v_mfma_f32_16x16x32_bf16 v[40:43], v[220:223], v[196:199], v[40:43]
	v_mfma_f32_16x16x32_bf16 v[32:35], v[228:231], v[196:199], v[32:35]
	v_mfma_f32_16x16x32_bf16 v[24:27], v[220:223], v[204:207], v[24:27]
	v_mfma_f32_16x16x32_bf16 v[16:19], v[228:231], v[204:207], v[16:19]
	v_mfma_f32_16x16x32_bf16 v[8:11], v[220:223], v[212:215], v[8:11]
	v_mfma_f32_16x16x32_bf16 v[0:3], v[228:231], v[212:215], v[0:3]
	s_setprio 0
	s_add_i32 s76, 0, 0x18000
	v_add_u32_e32 v150, s76, v179
	s_barrier
	s_branch .Lg359_mid
.LBB0_359:
	ds_read_b128 v[128:131], v181
	ds_read_b128 v[132:135], v181 offset:1024
	ds_read_b128 v[136:139], v181 offset:2048
	ds_read_b128 v[166:169], v181 offset:3072
	s_add_u32 s38, s8, 0xfffc0080
	s_addc_u32 s39, s9, -1
	s_cmp_eq_u32 s75, 12
	s_cselect_b32 s41, s21, s39
	s_cselect_b32 s40, s71, s38
	s_cselect_b32 s39, s19, s74
	s_cselect_b32 s38, s72, s73
	s_add_i32 m0, s37, 0xc000
	ds_read_b128 v[170:173], v182
	ds_read_b128 v[174:177], v182 offset:1024
	ds_read_b128 v[192:195], v182 offset:2048
	ds_read_b128 v[196:199], v182 offset:3072
	ds_read_b128 v[200:203], v182 offset:4096
	ds_read_b128 v[204:207], v182 offset:5120
	ds_read_b128 v[208:211], v182 offset:6144
	ds_read_b128 v[212:215], v182 offset:7168
	global_load_lds_dwordx4 v158, s[8:9]
	s_add_i32 m0, s37, 0xe000
	s_nop 0
	global_load_lds_dwordx4 v160, s[8:9]
	s_waitcnt lgkmcnt(8)
	s_barrier
	s_waitcnt lgkmcnt(0)
	s_setprio 1
	s_waitcnt lgkmcnt(0)
	v_mfma_f32_16x16x32_bf16 v[124:127], v[128:131], v[170:173], v[124:127]
	v_mfma_f32_16x16x32_bf16 v[116:119], v[136:139], v[170:173], v[116:119]
	v_mfma_f32_16x16x32_bf16 v[108:111], v[128:131], v[192:195], v[108:111]
	v_mfma_f32_16x16x32_bf16 v[100:103], v[136:139], v[192:195], v[100:103]
	v_mfma_f32_16x16x32_bf16 v[92:95], v[128:131], v[200:203], v[92:95]
	v_mfma_f32_16x16x32_bf16 v[84:87], v[136:139], v[200:203], v[84:87]
	v_mfma_f32_16x16x32_bf16 v[76:79], v[128:131], v[208:211], v[76:79]
	v_mfma_f32_16x16x32_bf16 v[68:71], v[136:139], v[208:211], v[68:71]
	v_mfma_f32_16x16x32_bf16 v[124:127], v[132:135], v[174:177], v[124:127]
	v_mfma_f32_16x16x32_bf16 v[116:119], v[166:169], v[174:177], v[116:119]
	v_mfma_f32_16x16x32_bf16 v[108:111], v[132:135], v[196:199], v[108:111]
	v_mfma_f32_16x16x32_bf16 v[100:103], v[166:169], v[196:199], v[100:103]
	v_mfma_f32_16x16x32_bf16 v[92:95], v[132:135], v[204:207], v[92:95]
	v_mfma_f32_16x16x32_bf16 v[84:87], v[166:169], v[204:207], v[84:87]
	v_mfma_f32_16x16x32_bf16 v[76:79], v[132:135], v[212:215], v[76:79]
	v_mfma_f32_16x16x32_bf16 v[68:71], v[166:169], v[212:215], v[68:71]
	s_setprio 0
	s_barrier
	s_add_i32 s76, s63, s46
	s_add_u32 s80, s38, 0x80
	s_addc_u32 s81, s39, 0
	s_mov_b32 m0, s76
	ds_read_b128 v[216:219], v183
	ds_read_b128 v[220:223], v183 offset:1024
	ds_read_b128 v[224:227], v183 offset:2048
	ds_read_b128 v[228:231], v183 offset:3072
	global_load_lds_dwordx4 v144, s[38:39]
	s_add_i32 m0, s76, 0x2000
	s_nop 0
	global_load_lds_dwordx4 v148, s[38:39]
	s_waitcnt vmcnt(10)
	s_barrier
	s_waitcnt lgkmcnt(0)
	s_setprio 1
	s_waitcnt lgkmcnt(0)
	v_mfma_f32_16x16x32_bf16 v[120:123], v[216:219], v[170:173], v[120:123]
	v_mfma_f32_16x16x32_bf16 v[112:115], v[224:227], v[170:173], v[112:115]
	v_mfma_f32_16x16x32_bf16 v[104:107], v[216:219], v[192:195], v[104:107]
	v_mfma_f32_16x16x32_bf16 v[96:99], v[224:227], v[192:195], v[96:99]
	v_mfma_f32_16x16x32_bf16 v[88:91], v[216:219], v[200:203], v[88:91]
	v_mfma_f32_16x16x32_bf16 v[80:83], v[224:227], v[200:203], v[80:83]
	v_mfma_f32_16x16x32_bf16 v[72:75], v[216:219], v[208:211], v[72:75]
	v_mfma_f32_16x16x32_bf16 v[64:67], v[224:227], v[208:211], v[64:67]
	v_mfma_f32_16x16x32_bf16 v[120:123], v[220:223], v[174:177], v[120:123]
	v_mfma_f32_16x16x32_bf16 v[112:115], v[228:231], v[174:177], v[112:115]
	v_mfma_f32_16x16x32_bf16 v[104:107], v[220:223], v[196:199], v[104:107]
	v_mfma_f32_16x16x32_bf16 v[96:99], v[228:231], v[196:199], v[96:99]
	v_mfma_f32_16x16x32_bf16 v[88:91], v[220:223], v[204:207], v[88:91]
	v_mfma_f32_16x16x32_bf16 v[80:83], v[228:231], v[204:207], v[80:83]
	v_mfma_f32_16x16x32_bf16 v[72:75], v[220:223], v[212:215], v[72:75]
	v_mfma_f32_16x16x32_bf16 v[64:67], v[228:231], v[212:215], v[64:67]
	s_setprio 0
	s_mov_b32 m0, s37
	s_add_u32 s82, s40, 0x80
	s_addc_u32 s83, s41, 0
	s_barrier
	ds_read_b128 v[170:173], v182 offset:16384
	ds_read_b128 v[174:177], v182 offset:17408
	ds_read_b128 v[192:195], v182 offset:18432
	ds_read_b128 v[196:199], v182 offset:19456
	ds_read_b128 v[200:203], v182 offset:20480
	ds_read_b128 v[204:207], v182 offset:21504
	ds_read_b128 v[208:211], v182 offset:22528
	ds_read_b128 v[212:215], v182 offset:23552
	global_load_lds_dwordx4 v142, s[40:41]
	s_mov_b32 m0, s51
	s_nop 0
	global_load_lds_dwordx4 v146, s[40:41]
	s_barrier
	s_waitcnt lgkmcnt(0)
	s_setprio 1
	s_waitcnt lgkmcnt(0)
	v_mfma_f32_16x16x32_bf16 v[60:63], v[128:131], v[170:173], v[60:63]
	v_mfma_f32_16x16x32_bf16 v[52:55], v[136:139], v[170:173], v[52:55]
	v_mfma_f32_16x16x32_bf16 v[44:47], v[128:131], v[192:195], v[44:47]
	v_mfma_f32_16x16x32_bf16 v[36:39], v[136:139], v[192:195], v[36:39]
	v_mfma_f32_16x16x32_bf16 v[28:31], v[128:131], v[200:203], v[28:31]
	v_mfma_f32_16x16x32_bf16 v[20:23], v[136:139], v[200:203], v[20:23]
	v_mfma_f32_16x16x32_bf16 v[12:15], v[128:131], v[208:211], v[12:15]
	v_mfma_f32_16x16x32_bf16 v[4:7], v[136:139], v[208:211], v[4:7]
	v_mfma_f32_16x16x32_bf16 v[60:63], v[132:135], v[174:177], v[60:63]
	v_mfma_f32_16x16x32_bf16 v[52:55], v[166:169], v[174:177], v[52:55]
	v_mfma_f32_16x16x32_bf16 v[44:47], v[132:135], v[196:199], v[44:47]
	v_mfma_f32_16x16x32_bf16 v[36:39], v[166:169], v[196:199], v[36:39]
	v_mfma_f32_16x16x32_bf16 v[28:31], v[132:135], v[204:207], v[28:31]
	v_mfma_f32_16x16x32_bf16 v[20:23], v[166:169], v[204:207], v[20:23]
	v_mfma_f32_16x16x32_bf16 v[12:15], v[132:135], v[212:215], v[12:15]
	v_mfma_f32_16x16x32_bf16 v[4:7], v[166:169], v[212:215], v[4:7]
	s_setprio 0
	s_barrier
	s_add_u32 s76, s38, 0x40000
	s_addc_u32 s77, s39, 0
	s_add_i32 s78, s64, s46
	s_mov_b32 m0, s78
	s_nop 0
	global_load_lds_dwordx4 v144, s[76:77]
	s_add_i32 m0, s78, 0x2000
	s_nop 0
	global_load_lds_dwordx4 v148, s[76:77]
	s_waitcnt vmcnt(8)
	s_barrier
	s_setprio 1
	v_mfma_f32_16x16x32_bf16 v[56:59], v[216:219], v[170:173], v[56:59]
	v_mfma_f32_16x16x32_bf16 v[48:51], v[224:227], v[170:173], v[48:51]
	v_mfma_f32_16x16x32_bf16 v[40:43], v[216:219], v[192:195], v[40:43]
	v_mfma_f32_16x16x32_bf16 v[32:35], v[224:227], v[192:195], v[32:35]
	v_mfma_f32_16x16x32_bf16 v[24:27], v[216:219], v[200:203], v[24:27]
	v_mfma_f32_16x16x32_bf16 v[16:19], v[224:227], v[200:203], v[16:19]
	v_mfma_f32_16x16x32_bf16 v[8:11], v[216:219], v[208:211], v[8:11]
	v_mfma_f32_16x16x32_bf16 v[0:3], v[224:227], v[208:211], v[0:3]
	v_mfma_f32_16x16x32_bf16 v[56:59], v[220:223], v[174:177], v[56:59]
	v_mfma_f32_16x16x32_bf16 v[48:51], v[228:231], v[174:177], v[48:51]
	v_mfma_f32_16x16x32_bf16 v[40:43], v[220:223], v[196:199], v[40:43]
	v_mfma_f32_16x16x32_bf16 v[32:35], v[228:231], v[196:199], v[32:35]
	v_mfma_f32_16x16x32_bf16 v[24:27], v[220:223], v[204:207], v[24:27]
	v_mfma_f32_16x16x32_bf16 v[16:19], v[228:231], v[204:207], v[16:19]
	v_mfma_f32_16x16x32_bf16 v[8:11], v[220:223], v[212:215], v[8:11]
	v_mfma_f32_16x16x32_bf16 v[0:3], v[228:231], v[212:215], v[0:3]
	s_setprio 0
	s_add_i32 s76, 0, 0x18000
	v_add_u32_e32 v150, s76, v179
	s_barrier
.Lg359_mid:
	ds_read_b128 v[128:131], v150
	ds_read_b128 v[132:135], v150 offset:1024
	ds_read_b128 v[136:139], v150 offset:2048
	ds_read_b128 v[166:169], v150 offset:3072
	s_add_u32 s40, s40, 0x40000
	s_addc_u32 s41, s41, 0
	s_mov_b32 m0, s52
	ds_read_b128 v[170:173], v182 offset:32768
	ds_read_b128 v[174:177], v182 offset:33792
	ds_read_b128 v[192:195], v182 offset:34816
	ds_read_b128 v[196:199], v182 offset:35840
	ds_read_b128 v[200:203], v182 offset:36864
	ds_read_b128 v[204:207], v182 offset:37888
	ds_read_b128 v[208:211], v182 offset:38912
	ds_read_b128 v[212:215], v182 offset:39936
	global_load_lds_dwordx4 v142, s[40:41]
	s_mov_b32 m0, s53
	s_nop 0
	global_load_lds_dwordx4 v146, s[40:41]
	s_waitcnt lgkmcnt(8)
	s_barrier
	s_waitcnt lgkmcnt(0)
	s_setprio 1
	s_waitcnt lgkmcnt(0)
	v_mfma_f32_16x16x32_bf16 v[124:127], v[128:131], v[170:173], v[124:127]
	v_mfma_f32_16x16x32_bf16 v[116:119], v[136:139], v[170:173], v[116:119]
	v_mfma_f32_16x16x32_bf16 v[108:111], v[128:131], v[192:195], v[108:111]
	v_mfma_f32_16x16x32_bf16 v[100:103], v[136:139], v[192:195], v[100:103]
	v_mfma_f32_16x16x32_bf16 v[92:95], v[128:131], v[200:203], v[92:95]
	v_mfma_f32_16x16x32_bf16 v[84:87], v[136:139], v[200:203], v[84:87]
	v_mfma_f32_16x16x32_bf16 v[76:79], v[128:131], v[208:211], v[76:79]
	v_mfma_f32_16x16x32_bf16 v[68:71], v[136:139], v[208:211], v[68:71]
	v_mfma_f32_16x16x32_bf16 v[124:127], v[132:135], v[174:177], v[124:127]
	v_mfma_f32_16x16x32_bf16 v[116:119], v[166:169], v[174:177], v[116:119]
	v_mfma_f32_16x16x32_bf16 v[108:111], v[132:135], v[196:199], v[108:111]
	v_mfma_f32_16x16x32_bf16 v[100:103], v[166:169], v[196:199], v[100:103]
	v_mfma_f32_16x16x32_bf16 v[92:95], v[132:135], v[204:207], v[92:95]
	v_mfma_f32_16x16x32_bf16 v[84:87], v[166:169], v[204:207], v[84:87]
	v_mfma_f32_16x16x32_bf16 v[76:79], v[132:135], v[212:215], v[76:79]
	v_mfma_f32_16x16x32_bf16 v[68:71], v[166:169], v[212:215], v[68:71]
	s_setprio 0
	s_barrier
	s_add_i32 s40, 0, 0x1c000
	s_add_i32 s41, s76, s46
	v_add_u32_e32 v150, s40, v179
	s_mov_b32 m0, s41
	ds_read_b128 v[216:219], v150
	ds_read_b128 v[220:223], v150 offset:1024
	ds_read_b128 v[224:227], v150 offset:2048
	ds_read_b128 v[228:231], v150 offset:3072
	global_load_lds_dwordx4 v144, s[80:81]
	s_add_i32 m0, s41, 0x2000
	s_nop 0
	global_load_lds_dwordx4 v148, s[80:81]
	s_waitcnt vmcnt(10)
	s_barrier
	s_waitcnt lgkmcnt(0)
	s_setprio 1
	s_waitcnt lgkmcnt(0)
	v_mfma_f32_16x16x32_bf16 v[120:123], v[216:219], v[170:173], v[120:123]
	v_mfma_f32_16x16x32_bf16 v[112:115], v[224:227], v[170:173], v[112:115]
	v_mfma_f32_16x16x32_bf16 v[104:107], v[216:219], v[192:195], v[104:107]
	v_mfma_f32_16x16x32_bf16 v[96:99], v[224:227], v[192:195], v[96:99]
	v_mfma_f32_16x16x32_bf16 v[88:91], v[216:219], v[200:203], v[88:91]
	v_mfma_f32_16x16x32_bf16 v[80:83], v[224:227], v[200:203], v[80:83]
	v_mfma_f32_16x16x32_bf16 v[72:75], v[216:219], v[208:211], v[72:75]
	v_mfma_f32_16x16x32_bf16 v[64:67], v[224:227], v[208:211], v[64:67]
	v_mfma_f32_16x16x32_bf16 v[120:123], v[220:223], v[174:177], v[120:123]
	v_mfma_f32_16x16x32_bf16 v[112:115], v[228:231], v[174:177], v[112:115]
	v_mfma_f32_16x16x32_bf16 v[104:107], v[220:223], v[196:199], v[104:107]
	v_mfma_f32_16x16x32_bf16 v[96:99], v[228:231], v[196:199], v[96:99]
	v_mfma_f32_16x16x32_bf16 v[88:91], v[220:223], v[204:207], v[88:91]
	v_mfma_f32_16x16x32_bf16 v[80:83], v[228:231], v[204:207], v[80:83]
	v_mfma_f32_16x16x32_bf16 v[72:75], v[220:223], v[212:215], v[72:75]
	v_mfma_f32_16x16x32_bf16 v[64:67], v[228:231], v[212:215], v[64:67]
	s_setprio 0
	s_mov_b32 m0, s55
	s_barrier
	ds_read_b128 v[170:173], v182 offset:49152
	ds_read_b128 v[174:177], v182 offset:50176
	ds_read_b128 v[192:195], v182 offset:51200
	ds_read_b128 v[196:199], v182 offset:52224
	ds_read_b128 v[200:203], v182 offset:53248
	ds_read_b128 v[204:207], v182 offset:54272
	ds_read_b128 v[208:211], v182 offset:55296
	ds_read_b128 v[212:215], v182 offset:56320
	global_load_lds_dwordx4 v142, s[82:83]
	s_mov_b32 m0, s56
	s_nop 0
	global_load_lds_dwordx4 v146, s[82:83]
	s_barrier
	s_waitcnt lgkmcnt(0)
	s_setprio 1
	s_waitcnt lgkmcnt(0)
	v_mfma_f32_16x16x32_bf16 v[60:63], v[128:131], v[170:173], v[60:63]
	v_mfma_f32_16x16x32_bf16 v[52:55], v[136:139], v[170:173], v[52:55]
	v_mfma_f32_16x16x32_bf16 v[44:47], v[128:131], v[192:195], v[44:47]
	v_mfma_f32_16x16x32_bf16 v[36:39], v[136:139], v[192:195], v[36:39]
	v_mfma_f32_16x16x32_bf16 v[28:31], v[128:131], v[200:203], v[28:31]
	v_mfma_f32_16x16x32_bf16 v[20:23], v[136:139], v[200:203], v[20:23]
	v_mfma_f32_16x16x32_bf16 v[12:15], v[128:131], v[208:211], v[12:15]
	v_mfma_f32_16x16x32_bf16 v[4:7], v[136:139], v[208:211], v[4:7]
	v_mfma_f32_16x16x32_bf16 v[60:63], v[132:135], v[174:177], v[60:63]
	v_mfma_f32_16x16x32_bf16 v[52:55], v[166:169], v[174:177], v[52:55]
	v_mfma_f32_16x16x32_bf16 v[44:47], v[132:135], v[196:199], v[44:47]
	v_mfma_f32_16x16x32_bf16 v[36:39], v[166:169], v[196:199], v[36:39]
	v_mfma_f32_16x16x32_bf16 v[28:31], v[132:135], v[204:207], v[28:31]
	v_mfma_f32_16x16x32_bf16 v[20:23], v[166:169], v[204:207], v[20:23]
	v_mfma_f32_16x16x32_bf16 v[12:15], v[132:135], v[212:215], v[12:15]
	v_mfma_f32_16x16x32_bf16 v[4:7], v[166:169], v[212:215], v[4:7]
	s_setprio 0
	s_barrier
	s_add_u32 s38, s38, 0x40080
	s_addc_u32 s39, s39, 0
	s_add_i32 s40, s40, s46
	s_mov_b32 m0, s40
	s_nop 0
	global_load_lds_dwordx4 v144, s[38:39]
	s_add_i32 m0, s40, 0x2000
	s_nop 0
	global_load_lds_dwordx4 v148, s[38:39]
	s_waitcnt vmcnt(8)
	s_barrier
	s_setprio 1
	v_mfma_f32_16x16x32_bf16 v[56:59], v[216:219], v[170:173], v[56:59]
	v_mfma_f32_16x16x32_bf16 v[48:51], v[224:227], v[170:173], v[48:51]
	v_mfma_f32_16x16x32_bf16 v[40:43], v[216:219], v[192:195], v[40:43]
	v_mfma_f32_16x16x32_bf16 v[32:35], v[224:227], v[192:195], v[32:35]
	v_mfma_f32_16x16x32_bf16 v[24:27], v[216:219], v[200:203], v[24:27]
	v_mfma_f32_16x16x32_bf16 v[16:19], v[224:227], v[200:203], v[16:19]
	v_mfma_f32_16x16x32_bf16 v[8:11], v[216:219], v[208:211], v[8:11]
	v_mfma_f32_16x16x32_bf16 v[0:3], v[224:227], v[208:211], v[0:3]
	v_mfma_f32_16x16x32_bf16 v[56:59], v[220:223], v[174:177], v[56:59]
	v_mfma_f32_16x16x32_bf16 v[48:51], v[228:231], v[174:177], v[48:51]
	v_mfma_f32_16x16x32_bf16 v[40:43], v[220:223], v[196:199], v[40:43]
	v_mfma_f32_16x16x32_bf16 v[32:35], v[228:231], v[196:199], v[32:35]
	v_mfma_f32_16x16x32_bf16 v[24:27], v[220:223], v[204:207], v[24:27]
	v_mfma_f32_16x16x32_bf16 v[16:19], v[228:231], v[204:207], v[16:19]
	v_mfma_f32_16x16x32_bf16 v[8:11], v[220:223], v[212:215], v[8:11]
	v_mfma_f32_16x16x32_bf16 v[0:3], v[228:231], v[212:215], v[0:3]
	s_setprio 0
	s_add_i32 s75, s75, 2
	s_add_u32 s8, s8, 0x100
	s_addc_u32 s9, s9, 0
	s_add_u32 s73, s73, 0x100
	s_addc_u32 s74, s74, 0
	s_cmp_gt_u32 s75, 13
	s_barrier
	s_cbranch_scc0 .LBB0_359
	s_cmpk_gt_u32 s45, 0xff
	s_cbranch_scc1 .Lg359_nox
	s_barrier

.Lg786_noy:
	ds_read_b128 v[144:147], v151
	ds_read_b128 v[156:159], v151 offset:1024
	ds_read_b128 v[160:163], v151 offset:2048
	ds_read_b128 v[164:167], v151 offset:3072
	s_add_u32 s30, s28, 0xfffc0080
	s_addc_u32 s31, s29, -1
	s_cmp_eq_u32 s61, 12
	s_cselect_b32 s35, s19, s31
	s_cselect_b32 s34, s57, s30
	s_cselect_b32 s31, s17, s60
	s_cselect_b32 s30, s58, s59
	s_add_i32 m0, s45, 0xc000
	ds_read_b128 v[168:171], v152
	ds_read_b128 v[172:175], v152 offset:1024
	ds_read_b128 v[176:179], v152 offset:2048
	ds_read_b128 v[180:183], v152 offset:3072
	ds_read_b128 v[184:187], v152 offset:4096
	ds_read_b128 v[188:191], v152 offset:5120
	ds_read_b128 v[192:195], v152 offset:6144
	ds_read_b128 v[196:199], v152 offset:7168
	global_load_lds_dwordx4 v136, s[28:29]
	s_add_i32 m0, s45, 0xe000
	s_nop 0
	global_load_lds_dwordx4 v138, s[28:29]
	s_waitcnt lgkmcnt(8)
	s_barrier
	s_waitcnt lgkmcnt(0)
	s_setprio 1
	s_waitcnt lgkmcnt(0)
	v_mfma_f32_16x16x32_bf16 v[124:127], v[144:147], v[168:171], 0
	v_mfma_f32_16x16x32_bf16 v[120:123], v[160:163], v[168:171], 0
	v_mfma_f32_16x16x32_bf16 v[108:111], v[144:147], v[176:179], 0
	v_mfma_f32_16x16x32_bf16 v[104:107], v[160:163], v[176:179], 0
	v_mfma_f32_16x16x32_bf16 v[92:95], v[144:147], v[184:187], 0
	v_mfma_f32_16x16x32_bf16 v[88:91], v[160:163], v[184:187], 0
	v_mfma_f32_16x16x32_bf16 v[76:79], v[144:147], v[192:195], 0
	v_mfma_f32_16x16x32_bf16 v[72:75], v[160:163], v[192:195], 0
	v_mfma_f32_16x16x32_bf16 v[124:127], v[156:159], v[172:175], v[124:127]
	v_mfma_f32_16x16x32_bf16 v[120:123], v[164:167], v[172:175], v[120:123]
	v_mfma_f32_16x16x32_bf16 v[108:111], v[156:159], v[180:183], v[108:111]
	v_mfma_f32_16x16x32_bf16 v[104:107], v[164:167], v[180:183], v[104:107]
	v_mfma_f32_16x16x32_bf16 v[92:95], v[156:159], v[188:191], v[92:95]
	v_mfma_f32_16x16x32_bf16 v[88:91], v[164:167], v[188:191], v[88:91]
	v_mfma_f32_16x16x32_bf16 v[76:79], v[156:159], v[196:199], v[76:79]
	v_mfma_f32_16x16x32_bf16 v[72:75], v[164:167], v[196:199], v[72:75]
	s_setprio 0
	s_barrier
	s_add_i32 s62, s53, s42
	s_add_u32 s80, s30, 0x80
	s_addc_u32 s81, s31, 0
	s_mov_b32 m0, s62
	ds_read_b128 v[200:203], v153
	ds_read_b128 v[204:207], v153 offset:1024
	ds_read_b128 v[208:211], v153 offset:2048
	ds_read_b128 v[212:215], v153 offset:3072
	global_load_lds_dwordx4 v132, s[30:31]
	s_add_i32 m0, s62, 0x2000
	s_nop 0
	global_load_lds_dwordx4 v128, s[30:31]
	s_waitcnt vmcnt(10)
	s_barrier
	s_waitcnt lgkmcnt(0)
	s_setprio 1
	s_waitcnt lgkmcnt(0)
	v_mfma_f32_16x16x32_bf16 v[116:119], v[200:203], v[168:171], 0
	v_mfma_f32_16x16x32_bf16 v[112:115], v[208:211], v[168:171], 0
	v_mfma_f32_16x16x32_bf16 v[100:103], v[200:203], v[176:179], 0
	v_mfma_f32_16x16x32_bf16 v[96:99], v[208:211], v[176:179], 0
	v_mfma_f32_16x16x32_bf16 v[84:87], v[200:203], v[184:187], 0
	v_mfma_f32_16x16x32_bf16 v[80:83], v[208:211], v[184:187], 0
	v_mfma_f32_16x16x32_bf16 v[68:71], v[200:203], v[192:195], 0
	v_mfma_f32_16x16x32_bf16 v[64:67], v[208:211], v[192:195], 0
	v_mfma_f32_16x16x32_bf16 v[116:119], v[204:207], v[172:175], v[116:119]
	v_mfma_f32_16x16x32_bf16 v[112:115], v[212:215], v[172:175], v[112:115]
	v_mfma_f32_16x16x32_bf16 v[100:103], v[204:207], v[180:183], v[100:103]
	v_mfma_f32_16x16x32_bf16 v[96:99], v[212:215], v[180:183], v[96:99]
	v_mfma_f32_16x16x32_bf16 v[84:87], v[204:207], v[188:191], v[84:87]
	v_mfma_f32_16x16x32_bf16 v[80:83], v[212:215], v[188:191], v[80:83]
	v_mfma_f32_16x16x32_bf16 v[68:71], v[204:207], v[196:199], v[68:71]
	v_mfma_f32_16x16x32_bf16 v[64:67], v[212:215], v[196:199], v[64:67]
	s_setprio 0
	s_mov_b32 m0, s45
	s_add_u32 s82, s34, 0x80
	s_addc_u32 s83, s35, 0
	s_barrier
	ds_read_b128 v[168:171], v152 offset:16384
	ds_read_b128 v[172:175], v152 offset:17408
	ds_read_b128 v[176:179], v152 offset:18432
	ds_read_b128 v[180:183], v152 offset:19456
	ds_read_b128 v[184:187], v152 offset:20480
	ds_read_b128 v[188:191], v152 offset:21504
	ds_read_b128 v[192:195], v152 offset:22528
	ds_read_b128 v[196:199], v152 offset:23552
	global_load_lds_dwordx4 v134, s[34:35]
	s_mov_b32 m0, s46
	s_nop 0
	global_load_lds_dwordx4 v130, s[34:35]
	s_barrier
	s_waitcnt lgkmcnt(0)
	s_setprio 1
	s_waitcnt lgkmcnt(0)
	v_mfma_f32_16x16x32_bf16 v[60:63], v[144:147], v[168:171], 0
	v_mfma_f32_16x16x32_bf16 v[56:59], v[160:163], v[168:171], 0
	v_mfma_f32_16x16x32_bf16 v[44:47], v[144:147], v[176:179], 0
	v_mfma_f32_16x16x32_bf16 v[40:43], v[160:163], v[176:179], 0
	v_mfma_f32_16x16x32_bf16 v[28:31], v[144:147], v[184:187], 0
	v_mfma_f32_16x16x32_bf16 v[24:27], v[160:163], v[184:187], 0
	v_mfma_f32_16x16x32_bf16 v[12:15], v[144:147], v[192:195], 0
	v_mfma_f32_16x16x32_bf16 v[8:11], v[160:163], v[192:195], 0
	v_mfma_f32_16x16x32_bf16 v[60:63], v[156:159], v[172:175], v[60:63]
	v_mfma_f32_16x16x32_bf16 v[56:59], v[164:167], v[172:175], v[56:59]
	v_mfma_f32_16x16x32_bf16 v[44:47], v[156:159], v[180:183], v[44:47]
	v_mfma_f32_16x16x32_bf16 v[40:43], v[164:167], v[180:183], v[40:43]
	v_mfma_f32_16x16x32_bf16 v[28:31], v[156:159], v[188:191], v[28:31]
	v_mfma_f32_16x16x32_bf16 v[24:27], v[164:167], v[188:191], v[24:27]
	v_mfma_f32_16x16x32_bf16 v[12:15], v[156:159], v[196:199], v[12:15]
	v_mfma_f32_16x16x32_bf16 v[8:11], v[164:167], v[196:199], v[8:11]
	s_setprio 0
	s_barrier
	s_add_u32 s62, s30, 0x40000
	s_addc_u32 s63, s31, 0
	s_add_i32 s64, s54, s42
	s_mov_b32 m0, s64
	s_nop 0
	global_load_lds_dwordx4 v132, s[62:63]
	s_add_i32 m0, s64, 0x2000
	s_nop 0
	global_load_lds_dwordx4 v128, s[62:63]
	s_waitcnt vmcnt(8)
	s_barrier
	s_setprio 1
	v_mfma_f32_16x16x32_bf16 v[52:55], v[200:203], v[168:171], 0
	v_mfma_f32_16x16x32_bf16 v[48:51], v[208:211], v[168:171], 0
	v_mfma_f32_16x16x32_bf16 v[36:39], v[200:203], v[176:179], 0
	v_mfma_f32_16x16x32_bf16 v[32:35], v[208:211], v[176:179], 0
	v_mfma_f32_16x16x32_bf16 v[20:23], v[200:203], v[184:187], 0
	v_mfma_f32_16x16x32_bf16 v[16:19], v[208:211], v[184:187], 0
	v_mfma_f32_16x16x32_bf16 v[4:7], v[200:203], v[192:195], 0
	v_mfma_f32_16x16x32_bf16 v[0:3], v[208:211], v[192:195], 0
	v_mfma_f32_16x16x32_bf16 v[52:55], v[204:207], v[172:175], v[52:55]
	v_mfma_f32_16x16x32_bf16 v[48:51], v[212:215], v[172:175], v[48:51]
	v_mfma_f32_16x16x32_bf16 v[36:39], v[204:207], v[180:183], v[36:39]
	v_mfma_f32_16x16x32_bf16 v[32:35], v[212:215], v[180:183], v[32:35]
	v_mfma_f32_16x16x32_bf16 v[20:23], v[204:207], v[188:191], v[20:23]
	v_mfma_f32_16x16x32_bf16 v[16:19], v[212:215], v[188:191], v[16:19]
	v_mfma_f32_16x16x32_bf16 v[4:7], v[204:207], v[196:199], v[4:7]
	v_mfma_f32_16x16x32_bf16 v[0:3], v[212:215], v[196:199], v[0:3]
	s_setprio 0
	s_add_i32 s62, 0, 0x18000
	v_add_u32_e32 v155, s62, v149
	s_barrier
	s_branch .Lg786_mid
.LBB0_786:
	ds_read_b128 v[144:147], v151
	ds_read_b128 v[156:159], v151 offset:1024
	ds_read_b128 v[160:163], v151 offset:2048
	ds_read_b128 v[164:167], v151 offset:3072
	s_add_u32 s30, s28, 0xfffc0080
	s_addc_u32 s31, s29, -1
	s_cmp_eq_u32 s61, 12
	s_cselect_b32 s35, s19, s31
	s_cselect_b32 s34, s57, s30
	s_cselect_b32 s31, s17, s60
	s_cselect_b32 s30, s58, s59
	s_add_i32 m0, s45, 0xc000
	ds_read_b128 v[168:171], v152
	ds_read_b128 v[172:175], v152 offset:1024
	ds_read_b128 v[176:179], v152 offset:2048
	ds_read_b128 v[180:183], v152 offset:3072
	ds_read_b128 v[184:187], v152 offset:4096
	ds_read_b128 v[188:191], v152 offset:5120
	ds_read_b128 v[192:195], v152 offset:6144
	ds_read_b128 v[196:199], v152 offset:7168
	global_load_lds_dwordx4 v136, s[28:29]
	s_add_i32 m0, s45, 0xe000
	s_nop 0
	global_load_lds_dwordx4 v138, s[28:29]
	s_waitcnt lgkmcnt(8)
	s_barrier
	s_waitcnt lgkmcnt(0)
	s_setprio 1
	s_waitcnt lgkmcnt(0)
	v_mfma_f32_16x16x32_bf16 v[124:127], v[144:147], v[168:171], v[124:127]
	v_mfma_f32_16x16x32_bf16 v[120:123], v[160:163], v[168:171], v[120:123]
	v_mfma_f32_16x16x32_bf16 v[108:111], v[144:147], v[176:179], v[108:111]
	v_mfma_f32_16x16x32_bf16 v[104:107], v[160:163], v[176:179], v[104:107]
	v_mfma_f32_16x16x32_bf16 v[92:95], v[144:147], v[184:187], v[92:95]
	v_mfma_f32_16x16x32_bf16 v[88:91], v[160:163], v[184:187], v[88:91]
	v_mfma_f32_16x16x32_bf16 v[76:79], v[144:147], v[192:195], v[76:79]
	v_mfma_f32_16x16x32_bf16 v[72:75], v[160:163], v[192:195], v[72:75]
	v_mfma_f32_16x16x32_bf16 v[124:127], v[156:159], v[172:175], v[124:127]
	v_mfma_f32_16x16x32_bf16 v[120:123], v[164:167], v[172:175], v[120:123]
	v_mfma_f32_16x16x32_bf16 v[108:111], v[156:159], v[180:183], v[108:111]
	v_mfma_f32_16x16x32_bf16 v[104:107], v[164:167], v[180:183], v[104:107]
	v_mfma_f32_16x16x32_bf16 v[92:95], v[156:159], v[188:191], v[92:95]
	v_mfma_f32_16x16x32_bf16 v[88:91], v[164:167], v[188:191], v[88:91]
	v_mfma_f32_16x16x32_bf16 v[76:79], v[156:159], v[196:199], v[76:79]
	v_mfma_f32_16x16x32_bf16 v[72:75], v[164:167], v[196:199], v[72:75]
	s_setprio 0
	s_barrier
	s_add_i32 s62, s53, s42
	s_add_u32 s80, s30, 0x80
	s_addc_u32 s81, s31, 0
	s_mov_b32 m0, s62
	ds_read_b128 v[200:203], v153
	ds_read_b128 v[204:207], v153 offset:1024
	ds_read_b128 v[208:211], v153 offset:2048
	ds_read_b128 v[212:215], v153 offset:3072
	global_load_lds_dwordx4 v132, s[30:31]
	s_add_i32 m0, s62, 0x2000
	s_nop 0
	global_load_lds_dwordx4 v128, s[30:31]
	s_waitcnt vmcnt(10)
	s_barrier
	s_waitcnt lgkmcnt(0)
	s_setprio 1
	s_waitcnt lgkmcnt(0)
	v_mfma_f32_16x16x32_bf16 v[116:119], v[200:203], v[168:171], v[116:119]
	v_mfma_f32_16x16x32_bf16 v[112:115], v[208:211], v[168:171], v[112:115]
	v_mfma_f32_16x16x32_bf16 v[100:103], v[200:203], v[176:179], v[100:103]
	v_mfma_f32_16x16x32_bf16 v[96:99], v[208:211], v[176:179], v[96:99]
	v_mfma_f32_16x16x32_bf16 v[84:87], v[200:203], v[184:187], v[84:87]
	v_mfma_f32_16x16x32_bf16 v[80:83], v[208:211], v[184:187], v[80:83]
	v_mfma_f32_16x16x32_bf16 v[68:71], v[200:203], v[192:195], v[68:71]
	v_mfma_f32_16x16x32_bf16 v[64:67], v[208:211], v[192:195], v[64:67]
	v_mfma_f32_16x16x32_bf16 v[116:119], v[204:207], v[172:175], v[116:119]
	v_mfma_f32_16x16x32_bf16 v[112:115], v[212:215], v[172:175], v[112:115]
	v_mfma_f32_16x16x32_bf16 v[100:103], v[204:207], v[180:183], v[100:103]
	v_mfma_f32_16x16x32_bf16 v[96:99], v[212:215], v[180:183], v[96:99]
	v_mfma_f32_16x16x32_bf16 v[84:87], v[204:207], v[188:191], v[84:87]
	v_mfma_f32_16x16x32_bf16 v[80:83], v[212:215], v[188:191], v[80:83]
	v_mfma_f32_16x16x32_bf16 v[68:71], v[204:207], v[196:199], v[68:71]
	v_mfma_f32_16x16x32_bf16 v[64:67], v[212:215], v[196:199], v[64:67]
	s_setprio 0
	s_mov_b32 m0, s45
	s_add_u32 s82, s34, 0x80
	s_addc_u32 s83, s35, 0
	s_barrier
	ds_read_b128 v[168:171], v152 offset:16384
	ds_read_b128 v[172:175], v152 offset:17408
	ds_read_b128 v[176:179], v152 offset:18432
	ds_read_b128 v[180:183], v152 offset:19456
	ds_read_b128 v[184:187], v152 offset:20480
	ds_read_b128 v[188:191], v152 offset:21504
	ds_read_b128 v[192:195], v152 offset:22528
	ds_read_b128 v[196:199], v152 offset:23552
	global_load_lds_dwordx4 v134, s[34:35]
	s_mov_b32 m0, s46
	s_nop 0
	global_load_lds_dwordx4 v130, s[34:35]
	s_barrier
	s_waitcnt lgkmcnt(0)
	s_setprio 1
	s_waitcnt lgkmcnt(0)
	v_mfma_f32_16x16x32_bf16 v[60:63], v[144:147], v[168:171], v[60:63]
	v_mfma_f32_16x16x32_bf16 v[56:59], v[160:163], v[168:171], v[56:59]
	v_mfma_f32_16x16x32_bf16 v[44:47], v[144:147], v[176:179], v[44:47]
	v_mfma_f32_16x16x32_bf16 v[40:43], v[160:163], v[176:179], v[40:43]
	v_mfma_f32_16x16x32_bf16 v[28:31], v[144:147], v[184:187], v[28:31]
	v_mfma_f32_16x16x32_bf16 v[24:27], v[160:163], v[184:187], v[24:27]
	v_mfma_f32_16x16x32_bf16 v[12:15], v[144:147], v[192:195], v[12:15]
	v_mfma_f32_16x16x32_bf16 v[8:11], v[160:163], v[192:195], v[8:11]
	v_mfma_f32_16x16x32_bf16 v[60:63], v[156:159], v[172:175], v[60:63]
	v_mfma_f32_16x16x32_bf16 v[56:59], v[164:167], v[172:175], v[56:59]
	v_mfma_f32_16x16x32_bf16 v[44:47], v[156:159], v[180:183], v[44:47]
	v_mfma_f32_16x16x32_bf16 v[40:43], v[164:167], v[180:183], v[40:43]
	v_mfma_f32_16x16x32_bf16 v[28:31], v[156:159], v[188:191], v[28:31]
	v_mfma_f32_16x16x32_bf16 v[24:27], v[164:167], v[188:191], v[24:27]
	v_mfma_f32_16x16x32_bf16 v[12:15], v[156:159], v[196:199], v[12:15]
	v_mfma_f32_16x16x32_bf16 v[8:11], v[164:167], v[196:199], v[8:11]
	s_setprio 0
	s_barrier
	s_add_u32 s62, s30, 0x40000
	s_addc_u32 s63, s31, 0
	s_add_i32 s64, s54, s42
	s_mov_b32 m0, s64
	s_nop 0
	global_load_lds_dwordx4 v132, s[62:63]
	s_add_i32 m0, s64, 0x2000
	s_nop 0
	global_load_lds_dwordx4 v128, s[62:63]
	s_waitcnt vmcnt(8)
	s_barrier
	s_setprio 1
	v_mfma_f32_16x16x32_bf16 v[52:55], v[200:203], v[168:171], v[52:55]
	v_mfma_f32_16x16x32_bf16 v[48:51], v[208:211], v[168:171], v[48:51]
	v_mfma_f32_16x16x32_bf16 v[36:39], v[200:203], v[176:179], v[36:39]
	v_mfma_f32_16x16x32_bf16 v[32:35], v[208:211], v[176:179], v[32:35]
	v_mfma_f32_16x16x32_bf16 v[20:23], v[200:203], v[184:187], v[20:23]
	v_mfma_f32_16x16x32_bf16 v[16:19], v[208:211], v[184:187], v[16:19]
	v_mfma_f32_16x16x32_bf16 v[4:7], v[200:203], v[192:195], v[4:7]
	v_mfma_f32_16x16x32_bf16 v[0:3], v[208:211], v[192:195], v[0:3]
	v_mfma_f32_16x16x32_bf16 v[52:55], v[204:207], v[172:175], v[52:55]
	v_mfma_f32_16x16x32_bf16 v[48:51], v[212:215], v[172:175], v[48:51]
	v_mfma_f32_16x16x32_bf16 v[36:39], v[204:207], v[180:183], v[36:39]
	v_mfma_f32_16x16x32_bf16 v[32:35], v[212:215], v[180:183], v[32:35]
	v_mfma_f32_16x16x32_bf16 v[20:23], v[204:207], v[188:191], v[20:23]
	v_mfma_f32_16x16x32_bf16 v[16:19], v[212:215], v[188:191], v[16:19]
	v_mfma_f32_16x16x32_bf16 v[4:7], v[204:207], v[196:199], v[4:7]
	v_mfma_f32_16x16x32_bf16 v[0:3], v[212:215], v[196:199], v[0:3]
	s_setprio 0
	s_add_i32 s62, 0, 0x18000
	v_add_u32_e32 v155, s62, v149
	s_barrier
.Lg786_mid:
	ds_read_b128 v[144:147], v155
	ds_read_b128 v[156:159], v155 offset:1024
	ds_read_b128 v[160:163], v155 offset:2048
	ds_read_b128 v[164:167], v155 offset:3072
	s_add_u32 s34, s34, 0x40000
	s_addc_u32 s35, s35, 0
	s_mov_b32 m0, s47
	ds_read_b128 v[168:171], v152 offset:32768
	ds_read_b128 v[172:175], v152 offset:33792
	ds_read_b128 v[176:179], v152 offset:34816
	ds_read_b128 v[180:183], v152 offset:35840
	ds_read_b128 v[184:187], v152 offset:36864
	ds_read_b128 v[188:191], v152 offset:37888
	ds_read_b128 v[192:195], v152 offset:38912
	ds_read_b128 v[196:199], v152 offset:39936
	global_load_lds_dwordx4 v134, s[34:35]
	s_mov_b32 m0, s48
	s_nop 0
	global_load_lds_dwordx4 v130, s[34:35]
	s_waitcnt lgkmcnt(8)
	s_barrier
	s_waitcnt lgkmcnt(0)
	s_setprio 1
	s_waitcnt lgkmcnt(0)
	v_mfma_f32_16x16x32_bf16 v[124:127], v[144:147], v[168:171], v[124:127]
	v_mfma_f32_16x16x32_bf16 v[120:123], v[160:163], v[168:171], v[120:123]
	v_mfma_f32_16x16x32_bf16 v[108:111], v[144:147], v[176:179], v[108:111]
	v_mfma_f32_16x16x32_bf16 v[104:107], v[160:163], v[176:179], v[104:107]
	v_mfma_f32_16x16x32_bf16 v[92:95], v[144:147], v[184:187], v[92:95]
	v_mfma_f32_16x16x32_bf16 v[88:91], v[160:163], v[184:187], v[88:91]
	v_mfma_f32_16x16x32_bf16 v[76:79], v[144:147], v[192:195], v[76:79]
	v_mfma_f32_16x16x32_bf16 v[72:75], v[160:163], v[192:195], v[72:75]
	v_mfma_f32_16x16x32_bf16 v[124:127], v[156:159], v[172:175], v[124:127]
	v_mfma_f32_16x16x32_bf16 v[120:123], v[164:167], v[172:175], v[120:123]
	v_mfma_f32_16x16x32_bf16 v[108:111], v[156:159], v[180:183], v[108:111]
	v_mfma_f32_16x16x32_bf16 v[104:107], v[164:167], v[180:183], v[104:107]
	v_mfma_f32_16x16x32_bf16 v[92:95], v[156:159], v[188:191], v[92:95]
	v_mfma_f32_16x16x32_bf16 v[88:91], v[164:167], v[188:191], v[88:91]
	v_mfma_f32_16x16x32_bf16 v[76:79], v[156:159], v[196:199], v[76:79]
	v_mfma_f32_16x16x32_bf16 v[72:75], v[164:167], v[196:199], v[72:75]
	s_setprio 0
	s_barrier
	s_add_i32 s34, 0, 0x1c000
	s_add_i32 s35, s62, s42
	v_add_u32_e32 v155, s34, v149
	s_mov_b32 m0, s35
	ds_read_b128 v[200:203], v155
	ds_read_b128 v[204:207], v155 offset:1024
	ds_read_b128 v[208:211], v155 offset:2048
	ds_read_b128 v[212:215], v155 offset:3072
	global_load_lds_dwordx4 v132, s[80:81]
	s_add_i32 m0, s35, 0x2000
	s_nop 0
	global_load_lds_dwordx4 v128, s[80:81]
	s_waitcnt vmcnt(10)
	s_barrier
	s_waitcnt lgkmcnt(0)
	s_setprio 1
	s_waitcnt lgkmcnt(0)
	v_mfma_f32_16x16x32_bf16 v[116:119], v[200:203], v[168:171], v[116:119]
	v_mfma_f32_16x16x32_bf16 v[112:115], v[208:211], v[168:171], v[112:115]
	v_mfma_f32_16x16x32_bf16 v[100:103], v[200:203], v[176:179], v[100:103]
	v_mfma_f32_16x16x32_bf16 v[96:99], v[208:211], v[176:179], v[96:99]
	v_mfma_f32_16x16x32_bf16 v[84:87], v[200:203], v[184:187], v[84:87]
	v_mfma_f32_16x16x32_bf16 v[80:83], v[208:211], v[184:187], v[80:83]
	v_mfma_f32_16x16x32_bf16 v[68:71], v[200:203], v[192:195], v[68:71]
	v_mfma_f32_16x16x32_bf16 v[64:67], v[208:211], v[192:195], v[64:67]
	v_mfma_f32_16x16x32_bf16 v[116:119], v[204:207], v[172:175], v[116:119]
	v_mfma_f32_16x16x32_bf16 v[112:115], v[212:215], v[172:175], v[112:115]
	v_mfma_f32_16x16x32_bf16 v[100:103], v[204:207], v[180:183], v[100:103]
	v_mfma_f32_16x16x32_bf16 v[96:99], v[212:215], v[180:183], v[96:99]
	v_mfma_f32_16x16x32_bf16 v[84:87], v[204:207], v[188:191], v[84:87]
	v_mfma_f32_16x16x32_bf16 v[80:83], v[212:215], v[188:191], v[80:83]
	v_mfma_f32_16x16x32_bf16 v[68:71], v[204:207], v[196:199], v[68:71]
	v_mfma_f32_16x16x32_bf16 v[64:67], v[212:215], v[196:199], v[64:67]
	s_setprio 0
	s_mov_b32 m0, s50
	s_barrier
	ds_read_b128 v[168:171], v152 offset:49152
	ds_read_b128 v[172:175], v152 offset:50176
	ds_read_b128 v[176:179], v152 offset:51200
	ds_read_b128 v[180:183], v152 offset:52224
	ds_read_b128 v[184:187], v152 offset:53248
	ds_read_b128 v[188:191], v152 offset:54272
	ds_read_b128 v[192:195], v152 offset:55296
	ds_read_b128 v[196:199], v152 offset:56320
	global_load_lds_dwordx4 v134, s[82:83]
	s_mov_b32 m0, s51
	s_nop 0
	global_load_lds_dwordx4 v130, s[82:83]
	s_barrier
	s_waitcnt lgkmcnt(0)
	s_setprio 1
	s_waitcnt lgkmcnt(0)
	v_mfma_f32_16x16x32_bf16 v[60:63], v[144:147], v[168:171], v[60:63]
	v_mfma_f32_16x16x32_bf16 v[56:59], v[160:163], v[168:171], v[56:59]
	v_mfma_f32_16x16x32_bf16 v[44:47], v[144:147], v[176:179], v[44:47]
	v_mfma_f32_16x16x32_bf16 v[40:43], v[160:163], v[176:179], v[40:43]
	v_mfma_f32_16x16x32_bf16 v[28:31], v[144:147], v[184:187], v[28:31]
	v_mfma_f32_16x16x32_bf16 v[24:27], v[160:163], v[184:187], v[24:27]
	v_mfma_f32_16x16x32_bf16 v[12:15], v[144:147], v[192:195], v[12:15]
	v_mfma_f32_16x16x32_bf16 v[8:11], v[160:163], v[192:195], v[8:11]
	v_mfma_f32_16x16x32_bf16 v[60:63], v[156:159], v[172:175], v[60:63]
	v_mfma_f32_16x16x32_bf16 v[56:59], v[164:167], v[172:175], v[56:59]
	v_mfma_f32_16x16x32_bf16 v[44:47], v[156:159], v[180:183], v[44:47]
	v_mfma_f32_16x16x32_bf16 v[40:43], v[164:167], v[180:183], v[40:43]
	v_mfma_f32_16x16x32_bf16 v[28:31], v[156:159], v[188:191], v[28:31]
	v_mfma_f32_16x16x32_bf16 v[24:27], v[164:167], v[188:191], v[24:27]
	v_mfma_f32_16x16x32_bf16 v[12:15], v[156:159], v[196:199], v[12:15]
	v_mfma_f32_16x16x32_bf16 v[8:11], v[164:167], v[196:199], v[8:11]
	s_setprio 0
	s_barrier
	s_add_u32 s30, s30, 0x40080
	s_addc_u32 s31, s31, 0
	s_add_i32 s34, s34, s42
	s_mov_b32 m0, s34
	s_nop 0
	global_load_lds_dwordx4 v132, s[30:31]
	s_add_i32 m0, s34, 0x2000
	s_nop 0
	global_load_lds_dwordx4 v128, s[30:31]
	s_waitcnt vmcnt(8)
	s_barrier
	s_setprio 1
	v_mfma_f32_16x16x32_bf16 v[52:55], v[200:203], v[168:171], v[52:55]
	v_mfma_f32_16x16x32_bf16 v[48:51], v[208:211], v[168:171], v[48:51]
	v_mfma_f32_16x16x32_bf16 v[36:39], v[200:203], v[176:179], v[36:39]
	v_mfma_f32_16x16x32_bf16 v[32:35], v[208:211], v[176:179], v[32:35]
	v_mfma_f32_16x16x32_bf16 v[20:23], v[200:203], v[184:187], v[20:23]
	v_mfma_f32_16x16x32_bf16 v[16:19], v[208:211], v[184:187], v[16:19]
	v_mfma_f32_16x16x32_bf16 v[4:7], v[200:203], v[192:195], v[4:7]
	v_mfma_f32_16x16x32_bf16 v[0:3], v[208:211], v[192:195], v[0:3]
	v_mfma_f32_16x16x32_bf16 v[52:55], v[204:207], v[172:175], v[52:55]
	v_mfma_f32_16x16x32_bf16 v[48:51], v[212:215], v[172:175], v[48:51]
	v_mfma_f32_16x16x32_bf16 v[36:39], v[204:207], v[180:183], v[36:39]
	v_mfma_f32_16x16x32_bf16 v[32:35], v[212:215], v[180:183], v[32:35]
	v_mfma_f32_16x16x32_bf16 v[20:23], v[204:207], v[188:191], v[20:23]
	v_mfma_f32_16x16x32_bf16 v[16:19], v[212:215], v[188:191], v[16:19]
	v_mfma_f32_16x16x32_bf16 v[4:7], v[204:207], v[196:199], v[4:7]
	v_mfma_f32_16x16x32_bf16 v[0:3], v[212:215], v[196:199], v[0:3]
	s_setprio 0
	s_add_i32 s61, s61, 2
	s_add_u32 s28, s28, 0x100
	s_addc_u32 s29, s29, 0
	s_add_u32 s59, s59, 0x100
	s_addc_u32 s60, s60, 0
	s_cmp_gt_u32 s61, 13
	s_barrier
	s_cbranch_scc0 .LBB0_786
	v_lshl_add_u32 v146, s8, 8, v148
	v_ashrrev_i32_e32 v147, 31, v146
	v_lshl_or_b32 v144, s56, 8, v150
	v_lshlrev_b64 v[156:157], 11, v[146:147]
	v_ashrrev_i32_e32 v145, 31, v144
	v_lshl_add_u64 v[156:157], s[10:11], 0, v[156:157]
	v_lshl_add_u64 v[166:167], v[144:145], 1, v[156:157]
	global_load_dwordx4 v[158:161], v[166:167], off
	global_load_dwordx4 v[162:165], v[166:167], off offset:256
	s_mov_b64 s[84:85], 0x8000
	s_mov_b64 s[86:87], 0x28000
	v_lshl_add_u64 v[232:233], v[166:167], 0, s[84:85]
	global_load_dwordx4 v[176:179], v[232:233], off
	global_load_dwordx4 v[180:183], v[232:233], off offset:256
	v_lshl_add_u64 v[232:233], v[232:233], 0, s[84:85]
	global_load_dwordx4 v[184:187], v[232:233], off
	global_load_dwordx4 v[188:191], v[232:233], off offset:256
	v_lshl_add_u64 v[232:233], v[232:233], 0, s[84:85]
	global_load_dwordx4 v[192:195], v[232:233], off
	global_load_dwordx4 v[196:199], v[232:233], off offset:256
	v_lshl_add_u64 v[232:233], v[232:233], 0, s[86:87]
	global_load_dwordx4 v[200:203], v[232:233], off
	global_load_dwordx4 v[204:207], v[232:233], off offset:256
	v_lshl_add_u64 v[232:233], v[232:233], 0, s[84:85]
	global_load_dwordx4 v[208:211], v[232:233], off
	global_load_dwordx4 v[212:215], v[232:233], off offset:256
	v_lshl_add_u64 v[232:233], v[232:233], 0, s[84:85]
	global_load_dwordx4 v[216:219], v[232:233], off
	global_load_dwordx4 v[220:223], v[232:233], off offset:256
	v_lshl_add_u64 v[232:233], v[232:233], 0, s[84:85]
	global_load_dwordx4 v[224:227], v[232:233], off
	global_load_dwordx4 v[228:231], v[232:233], off offset:256
	s_cmpk_gt_u32 s37, 0xff
	s_cbranch_scc1 .Lg786_nox
	s_barrier

.Lg893_noy:
	ds_read_b128 v[152:155], v148
	ds_read_b128 v[156:159], v148 offset:1024
	ds_read_b128 v[160:163], v148 offset:2048
	ds_read_b128 v[164:167], v148 offset:3072
	s_add_u32 s26, s20, 0xfffc0080
	s_addc_u32 s27, s21, -1
	s_cmp_eq_u32 s57, 12
	s_cselect_b32 s29, s13, s27
	s_cselect_b32 s28, s53, s26
	s_cselect_b32 s27, s11, s56
	s_cselect_b32 s26, s54, s55
	s_add_i32 m0, s19, 0xc000
	ds_read_b128 v[168:171], v149
	ds_read_b128 v[172:175], v149 offset:1024
	ds_read_b128 v[176:179], v149 offset:2048
	ds_read_b128 v[180:183], v149 offset:3072
	ds_read_b128 v[184:187], v149 offset:4096
	ds_read_b128 v[188:191], v149 offset:5120
	ds_read_b128 v[192:195], v149 offset:6144
	ds_read_b128 v[196:199], v149 offset:7168
	global_load_lds_dwordx4 v136, s[20:21]
	s_add_i32 m0, s19, 0xe000
	s_nop 0
	global_load_lds_dwordx4 v138, s[20:21]
	s_waitcnt lgkmcnt(8)
	s_barrier
	s_waitcnt lgkmcnt(0)
	s_setprio 1
	s_waitcnt lgkmcnt(0)
	v_mfma_f32_16x16x32_bf16 v[124:127], v[152:155], v[168:171], 0
	v_mfma_f32_16x16x32_bf16 v[120:123], v[160:163], v[168:171], 0
	v_mfma_f32_16x16x32_bf16 v[108:111], v[152:155], v[176:179], 0
	v_mfma_f32_16x16x32_bf16 v[104:107], v[160:163], v[176:179], 0
	v_mfma_f32_16x16x32_bf16 v[92:95], v[152:155], v[184:187], 0
	v_mfma_f32_16x16x32_bf16 v[88:91], v[160:163], v[184:187], 0
	v_mfma_f32_16x16x32_bf16 v[76:79], v[152:155], v[192:195], 0
	v_mfma_f32_16x16x32_bf16 v[72:75], v[160:163], v[192:195], 0
	v_mfma_f32_16x16x32_bf16 v[124:127], v[156:159], v[172:175], v[124:127]
	v_mfma_f32_16x16x32_bf16 v[120:123], v[164:167], v[172:175], v[120:123]
	v_mfma_f32_16x16x32_bf16 v[108:111], v[156:159], v[180:183], v[108:111]
	v_mfma_f32_16x16x32_bf16 v[104:107], v[164:167], v[180:183], v[104:107]
	v_mfma_f32_16x16x32_bf16 v[92:95], v[156:159], v[188:191], v[92:95]
	v_mfma_f32_16x16x32_bf16 v[88:91], v[164:167], v[188:191], v[88:91]
	v_mfma_f32_16x16x32_bf16 v[76:79], v[156:159], v[196:199], v[76:79]
	v_mfma_f32_16x16x32_bf16 v[72:75], v[164:167], v[196:199], v[72:75]
	s_setprio 0
	s_barrier
	s_add_i32 s58, s47, s31
	s_add_u32 s80, s26, 0x80
	s_addc_u32 s81, s27, 0
	s_mov_b32 m0, s58
	ds_read_b128 v[200:203], v150
	ds_read_b128 v[204:207], v150 offset:1024
	ds_read_b128 v[208:211], v150 offset:2048
	ds_read_b128 v[212:215], v150 offset:3072
	global_load_lds_dwordx4 v132, s[26:27]
	s_add_i32 m0, s58, 0x2000
	s_nop 0
	global_load_lds_dwordx4 v128, s[26:27]
	s_waitcnt vmcnt(10)
	s_barrier
	s_waitcnt lgkmcnt(0)
	s_setprio 1
	s_waitcnt lgkmcnt(0)
	v_mfma_f32_16x16x32_bf16 v[116:119], v[200:203], v[168:171], 0
	v_mfma_f32_16x16x32_bf16 v[112:115], v[208:211], v[168:171], 0
	v_mfma_f32_16x16x32_bf16 v[100:103], v[200:203], v[176:179], 0
	v_mfma_f32_16x16x32_bf16 v[96:99], v[208:211], v[176:179], 0
	v_mfma_f32_16x16x32_bf16 v[84:87], v[200:203], v[184:187], 0
	v_mfma_f32_16x16x32_bf16 v[80:83], v[208:211], v[184:187], 0
	v_mfma_f32_16x16x32_bf16 v[68:71], v[200:203], v[192:195], 0
	v_mfma_f32_16x16x32_bf16 v[64:67], v[208:211], v[192:195], 0
	v_mfma_f32_16x16x32_bf16 v[116:119], v[204:207], v[172:175], v[116:119]
	v_mfma_f32_16x16x32_bf16 v[112:115], v[212:215], v[172:175], v[112:115]
	v_mfma_f32_16x16x32_bf16 v[100:103], v[204:207], v[180:183], v[100:103]
	v_mfma_f32_16x16x32_bf16 v[96:99], v[212:215], v[180:183], v[96:99]
	v_mfma_f32_16x16x32_bf16 v[84:87], v[204:207], v[188:191], v[84:87]
	v_mfma_f32_16x16x32_bf16 v[80:83], v[212:215], v[188:191], v[80:83]
	v_mfma_f32_16x16x32_bf16 v[68:71], v[204:207], v[196:199], v[68:71]
	v_mfma_f32_16x16x32_bf16 v[64:67], v[212:215], v[196:199], v[64:67]
	s_setprio 0
	s_mov_b32 m0, s19
	s_add_u32 s82, s28, 0x80
	s_addc_u32 s83, s29, 0
	s_barrier
	ds_read_b128 v[168:171], v149 offset:16384
	ds_read_b128 v[172:175], v149 offset:17408
	ds_read_b128 v[176:179], v149 offset:18432
	ds_read_b128 v[180:183], v149 offset:19456
	ds_read_b128 v[184:187], v149 offset:20480
	ds_read_b128 v[188:191], v149 offset:21504
	ds_read_b128 v[192:195], v149 offset:22528
	ds_read_b128 v[196:199], v149 offset:23552
	global_load_lds_dwordx4 v134, s[28:29]
	s_mov_b32 m0, s42
	s_nop 0
	global_load_lds_dwordx4 v130, s[28:29]
	s_barrier
	s_waitcnt lgkmcnt(0)
	s_setprio 1
	s_waitcnt lgkmcnt(0)
	v_mfma_f32_16x16x32_bf16 v[60:63], v[152:155], v[168:171], 0
	v_mfma_f32_16x16x32_bf16 v[56:59], v[160:163], v[168:171], 0
	v_mfma_f32_16x16x32_bf16 v[44:47], v[152:155], v[176:179], 0
	v_mfma_f32_16x16x32_bf16 v[40:43], v[160:163], v[176:179], 0
	v_mfma_f32_16x16x32_bf16 v[28:31], v[152:155], v[184:187], 0
	v_mfma_f32_16x16x32_bf16 v[24:27], v[160:163], v[184:187], 0
	v_mfma_f32_16x16x32_bf16 v[12:15], v[152:155], v[192:195], 0
	v_mfma_f32_16x16x32_bf16 v[8:11], v[160:163], v[192:195], 0
	v_mfma_f32_16x16x32_bf16 v[60:63], v[156:159], v[172:175], v[60:63]
	v_mfma_f32_16x16x32_bf16 v[56:59], v[164:167], v[172:175], v[56:59]
	v_mfma_f32_16x16x32_bf16 v[44:47], v[156:159], v[180:183], v[44:47]
	v_mfma_f32_16x16x32_bf16 v[40:43], v[164:167], v[180:183], v[40:43]
	v_mfma_f32_16x16x32_bf16 v[28:31], v[156:159], v[188:191], v[28:31]
	v_mfma_f32_16x16x32_bf16 v[24:27], v[164:167], v[188:191], v[24:27]
	v_mfma_f32_16x16x32_bf16 v[12:15], v[156:159], v[196:199], v[12:15]
	v_mfma_f32_16x16x32_bf16 v[8:11], v[164:167], v[196:199], v[8:11]
	s_setprio 0
	s_barrier
	s_add_u32 s58, s26, 0x40000
	s_addc_u32 s59, s27, 0
	s_add_i32 s60, s48, s31
	s_mov_b32 m0, s60
	s_nop 0
	global_load_lds_dwordx4 v132, s[58:59]
	s_add_i32 m0, s60, 0x2000
	s_nop 0
	global_load_lds_dwordx4 v128, s[58:59]
	s_waitcnt vmcnt(8)
	s_barrier
	s_setprio 1
	v_mfma_f32_16x16x32_bf16 v[52:55], v[200:203], v[168:171], 0
	v_mfma_f32_16x16x32_bf16 v[48:51], v[208:211], v[168:171], 0
	v_mfma_f32_16x16x32_bf16 v[36:39], v[200:203], v[176:179], 0
	v_mfma_f32_16x16x32_bf16 v[32:35], v[208:211], v[176:179], 0
	v_mfma_f32_16x16x32_bf16 v[20:23], v[200:203], v[184:187], 0
	v_mfma_f32_16x16x32_bf16 v[16:19], v[208:211], v[184:187], 0
	v_mfma_f32_16x16x32_bf16 v[4:7], v[200:203], v[192:195], 0
	v_mfma_f32_16x16x32_bf16 v[0:3], v[208:211], v[192:195], 0
	v_mfma_f32_16x16x32_bf16 v[52:55], v[204:207], v[172:175], v[52:55]
	v_mfma_f32_16x16x32_bf16 v[48:51], v[212:215], v[172:175], v[48:51]
	v_mfma_f32_16x16x32_bf16 v[36:39], v[204:207], v[180:183], v[36:39]
	v_mfma_f32_16x16x32_bf16 v[32:35], v[212:215], v[180:183], v[32:35]
	v_mfma_f32_16x16x32_bf16 v[20:23], v[204:207], v[188:191], v[20:23]
	v_mfma_f32_16x16x32_bf16 v[16:19], v[212:215], v[188:191], v[16:19]
	v_mfma_f32_16x16x32_bf16 v[4:7], v[204:207], v[196:199], v[4:7]
	v_mfma_f32_16x16x32_bf16 v[0:3], v[212:215], v[196:199], v[0:3]
	s_setprio 0
	s_add_i32 s58, 0, 0x18000
	v_add_u32_e32 v151, s58, v145
	s_barrier
	s_branch .Lg893_mid
.LBB0_893:
	ds_read_b128 v[152:155], v148
	ds_read_b128 v[156:159], v148 offset:1024
	ds_read_b128 v[160:163], v148 offset:2048
	ds_read_b128 v[164:167], v148 offset:3072
	s_add_u32 s26, s20, 0xfffc0080
	s_addc_u32 s27, s21, -1
	s_cmp_eq_u32 s57, 12
	s_cselect_b32 s29, s13, s27
	s_cselect_b32 s28, s53, s26
	s_cselect_b32 s27, s11, s56
	s_cselect_b32 s26, s54, s55
	s_add_i32 m0, s19, 0xc000
	ds_read_b128 v[168:171], v149
	ds_read_b128 v[172:175], v149 offset:1024
	ds_read_b128 v[176:179], v149 offset:2048
	ds_read_b128 v[180:183], v149 offset:3072
	ds_read_b128 v[184:187], v149 offset:4096
	ds_read_b128 v[188:191], v149 offset:5120
	ds_read_b128 v[192:195], v149 offset:6144
	ds_read_b128 v[196:199], v149 offset:7168
	global_load_lds_dwordx4 v136, s[20:21]
	s_add_i32 m0, s19, 0xe000
	s_nop 0
	global_load_lds_dwordx4 v138, s[20:21]
	s_waitcnt lgkmcnt(8)
	s_barrier
	s_waitcnt lgkmcnt(0)
	s_setprio 1
	s_waitcnt lgkmcnt(0)
	v_mfma_f32_16x16x32_bf16 v[124:127], v[152:155], v[168:171], v[124:127]
	v_mfma_f32_16x16x32_bf16 v[120:123], v[160:163], v[168:171], v[120:123]
	v_mfma_f32_16x16x32_bf16 v[108:111], v[152:155], v[176:179], v[108:111]
	v_mfma_f32_16x16x32_bf16 v[104:107], v[160:163], v[176:179], v[104:107]
	v_mfma_f32_16x16x32_bf16 v[92:95], v[152:155], v[184:187], v[92:95]
	v_mfma_f32_16x16x32_bf16 v[88:91], v[160:163], v[184:187], v[88:91]
	v_mfma_f32_16x16x32_bf16 v[76:79], v[152:155], v[192:195], v[76:79]
	v_mfma_f32_16x16x32_bf16 v[72:75], v[160:163], v[192:195], v[72:75]
	v_mfma_f32_16x16x32_bf16 v[124:127], v[156:159], v[172:175], v[124:127]
	v_mfma_f32_16x16x32_bf16 v[120:123], v[164:167], v[172:175], v[120:123]
	v_mfma_f32_16x16x32_bf16 v[108:111], v[156:159], v[180:183], v[108:111]
	v_mfma_f32_16x16x32_bf16 v[104:107], v[164:167], v[180:183], v[104:107]
	v_mfma_f32_16x16x32_bf16 v[92:95], v[156:159], v[188:191], v[92:95]
	v_mfma_f32_16x16x32_bf16 v[88:91], v[164:167], v[188:191], v[88:91]
	v_mfma_f32_16x16x32_bf16 v[76:79], v[156:159], v[196:199], v[76:79]
	v_mfma_f32_16x16x32_bf16 v[72:75], v[164:167], v[196:199], v[72:75]
	s_setprio 0
	s_barrier
	s_add_i32 s58, s47, s31
	s_add_u32 s80, s26, 0x80
	s_addc_u32 s81, s27, 0
	s_mov_b32 m0, s58
	ds_read_b128 v[200:203], v150
	ds_read_b128 v[204:207], v150 offset:1024
	ds_read_b128 v[208:211], v150 offset:2048
	ds_read_b128 v[212:215], v150 offset:3072
	global_load_lds_dwordx4 v132, s[26:27]
	s_add_i32 m0, s58, 0x2000
	s_nop 0
	global_load_lds_dwordx4 v128, s[26:27]
	s_waitcnt vmcnt(10)
	s_barrier
	s_waitcnt lgkmcnt(0)
	s_setprio 1
	s_waitcnt lgkmcnt(0)
	v_mfma_f32_16x16x32_bf16 v[116:119], v[200:203], v[168:171], v[116:119]
	v_mfma_f32_16x16x32_bf16 v[112:115], v[208:211], v[168:171], v[112:115]
	v_mfma_f32_16x16x32_bf16 v[100:103], v[200:203], v[176:179], v[100:103]
	v_mfma_f32_16x16x32_bf16 v[96:99], v[208:211], v[176:179], v[96:99]
	v_mfma_f32_16x16x32_bf16 v[84:87], v[200:203], v[184:187], v[84:87]
	v_mfma_f32_16x16x32_bf16 v[80:83], v[208:211], v[184:187], v[80:83]
	v_mfma_f32_16x16x32_bf16 v[68:71], v[200:203], v[192:195], v[68:71]
	v_mfma_f32_16x16x32_bf16 v[64:67], v[208:211], v[192:195], v[64:67]
	v_mfma_f32_16x16x32_bf16 v[116:119], v[204:207], v[172:175], v[116:119]
	v_mfma_f32_16x16x32_bf16 v[112:115], v[212:215], v[172:175], v[112:115]
	v_mfma_f32_16x16x32_bf16 v[100:103], v[204:207], v[180:183], v[100:103]
	v_mfma_f32_16x16x32_bf16 v[96:99], v[212:215], v[180:183], v[96:99]
	v_mfma_f32_16x16x32_bf16 v[84:87], v[204:207], v[188:191], v[84:87]
	v_mfma_f32_16x16x32_bf16 v[80:83], v[212:215], v[188:191], v[80:83]
	v_mfma_f32_16x16x32_bf16 v[68:71], v[204:207], v[196:199], v[68:71]
	v_mfma_f32_16x16x32_bf16 v[64:67], v[212:215], v[196:199], v[64:67]
	s_setprio 0
	s_mov_b32 m0, s19
	s_add_u32 s82, s28, 0x80
	s_addc_u32 s83, s29, 0
	s_barrier
	ds_read_b128 v[168:171], v149 offset:16384
	ds_read_b128 v[172:175], v149 offset:17408
	ds_read_b128 v[176:179], v149 offset:18432
	ds_read_b128 v[180:183], v149 offset:19456
	ds_read_b128 v[184:187], v149 offset:20480
	ds_read_b128 v[188:191], v149 offset:21504
	ds_read_b128 v[192:195], v149 offset:22528
	ds_read_b128 v[196:199], v149 offset:23552
	global_load_lds_dwordx4 v134, s[28:29]
	s_mov_b32 m0, s42
	s_nop 0
	global_load_lds_dwordx4 v130, s[28:29]
	s_barrier
	s_waitcnt lgkmcnt(0)
	s_setprio 1
	s_waitcnt lgkmcnt(0)
	v_mfma_f32_16x16x32_bf16 v[60:63], v[152:155], v[168:171], v[60:63]
	v_mfma_f32_16x16x32_bf16 v[56:59], v[160:163], v[168:171], v[56:59]
	v_mfma_f32_16x16x32_bf16 v[44:47], v[152:155], v[176:179], v[44:47]
	v_mfma_f32_16x16x32_bf16 v[40:43], v[160:163], v[176:179], v[40:43]
	v_mfma_f32_16x16x32_bf16 v[28:31], v[152:155], v[184:187], v[28:31]
	v_mfma_f32_16x16x32_bf16 v[24:27], v[160:163], v[184:187], v[24:27]
	v_mfma_f32_16x16x32_bf16 v[12:15], v[152:155], v[192:195], v[12:15]
	v_mfma_f32_16x16x32_bf16 v[8:11], v[160:163], v[192:195], v[8:11]
	v_mfma_f32_16x16x32_bf16 v[60:63], v[156:159], v[172:175], v[60:63]
	v_mfma_f32_16x16x32_bf16 v[56:59], v[164:167], v[172:175], v[56:59]
	v_mfma_f32_16x16x32_bf16 v[44:47], v[156:159], v[180:183], v[44:47]
	v_mfma_f32_16x16x32_bf16 v[40:43], v[164:167], v[180:183], v[40:43]
	v_mfma_f32_16x16x32_bf16 v[28:31], v[156:159], v[188:191], v[28:31]
	v_mfma_f32_16x16x32_bf16 v[24:27], v[164:167], v[188:191], v[24:27]
	v_mfma_f32_16x16x32_bf16 v[12:15], v[156:159], v[196:199], v[12:15]
	v_mfma_f32_16x16x32_bf16 v[8:11], v[164:167], v[196:199], v[8:11]
	s_setprio 0
	s_barrier
	s_add_u32 s58, s26, 0x40000
	s_addc_u32 s59, s27, 0
	s_add_i32 s60, s48, s31
	s_mov_b32 m0, s60
	s_nop 0
	global_load_lds_dwordx4 v132, s[58:59]
	s_add_i32 m0, s60, 0x2000
	s_nop 0
	global_load_lds_dwordx4 v128, s[58:59]
	s_waitcnt vmcnt(8)
	s_barrier
	s_setprio 1
	v_mfma_f32_16x16x32_bf16 v[52:55], v[200:203], v[168:171], v[52:55]
	v_mfma_f32_16x16x32_bf16 v[48:51], v[208:211], v[168:171], v[48:51]
	v_mfma_f32_16x16x32_bf16 v[36:39], v[200:203], v[176:179], v[36:39]
	v_mfma_f32_16x16x32_bf16 v[32:35], v[208:211], v[176:179], v[32:35]
	v_mfma_f32_16x16x32_bf16 v[20:23], v[200:203], v[184:187], v[20:23]
	v_mfma_f32_16x16x32_bf16 v[16:19], v[208:211], v[184:187], v[16:19]
	v_mfma_f32_16x16x32_bf16 v[4:7], v[200:203], v[192:195], v[4:7]
	v_mfma_f32_16x16x32_bf16 v[0:3], v[208:211], v[192:195], v[0:3]
	v_mfma_f32_16x16x32_bf16 v[52:55], v[204:207], v[172:175], v[52:55]
	v_mfma_f32_16x16x32_bf16 v[48:51], v[212:215], v[172:175], v[48:51]
	v_mfma_f32_16x16x32_bf16 v[36:39], v[204:207], v[180:183], v[36:39]
	v_mfma_f32_16x16x32_bf16 v[32:35], v[212:215], v[180:183], v[32:35]
	v_mfma_f32_16x16x32_bf16 v[20:23], v[204:207], v[188:191], v[20:23]
	v_mfma_f32_16x16x32_bf16 v[16:19], v[212:215], v[188:191], v[16:19]
	v_mfma_f32_16x16x32_bf16 v[4:7], v[204:207], v[196:199], v[4:7]
	v_mfma_f32_16x16x32_bf16 v[0:3], v[212:215], v[196:199], v[0:3]
	s_setprio 0
	s_add_i32 s58, 0, 0x18000
	v_add_u32_e32 v151, s58, v145
	s_barrier
.Lg893_mid:
	ds_read_b128 v[152:155], v151
	ds_read_b128 v[156:159], v151 offset:1024
	ds_read_b128 v[160:163], v151 offset:2048
	ds_read_b128 v[164:167], v151 offset:3072
	s_add_u32 s28, s28, 0x40000
	s_addc_u32 s29, s29, 0
	s_mov_b32 m0, s43
	ds_read_b128 v[168:171], v149 offset:32768
	ds_read_b128 v[172:175], v149 offset:33792
	ds_read_b128 v[176:179], v149 offset:34816
	ds_read_b128 v[180:183], v149 offset:35840
	ds_read_b128 v[184:187], v149 offset:36864
	ds_read_b128 v[188:191], v149 offset:37888
	ds_read_b128 v[192:195], v149 offset:38912
	ds_read_b128 v[196:199], v149 offset:39936
	global_load_lds_dwordx4 v134, s[28:29]
	s_mov_b32 m0, s44
	s_nop 0
	global_load_lds_dwordx4 v130, s[28:29]
	s_waitcnt lgkmcnt(8)
	s_barrier
	s_waitcnt lgkmcnt(0)
	s_setprio 1
	s_waitcnt lgkmcnt(0)
	v_mfma_f32_16x16x32_bf16 v[124:127], v[152:155], v[168:171], v[124:127]
	v_mfma_f32_16x16x32_bf16 v[120:123], v[160:163], v[168:171], v[120:123]
	v_mfma_f32_16x16x32_bf16 v[108:111], v[152:155], v[176:179], v[108:111]
	v_mfma_f32_16x16x32_bf16 v[104:107], v[160:163], v[176:179], v[104:107]
	v_mfma_f32_16x16x32_bf16 v[92:95], v[152:155], v[184:187], v[92:95]
	v_mfma_f32_16x16x32_bf16 v[88:91], v[160:163], v[184:187], v[88:91]
	v_mfma_f32_16x16x32_bf16 v[76:79], v[152:155], v[192:195], v[76:79]
	v_mfma_f32_16x16x32_bf16 v[72:75], v[160:163], v[192:195], v[72:75]
	v_mfma_f32_16x16x32_bf16 v[124:127], v[156:159], v[172:175], v[124:127]
	v_mfma_f32_16x16x32_bf16 v[120:123], v[164:167], v[172:175], v[120:123]
	v_mfma_f32_16x16x32_bf16 v[108:111], v[156:159], v[180:183], v[108:111]
	v_mfma_f32_16x16x32_bf16 v[104:107], v[164:167], v[180:183], v[104:107]
	v_mfma_f32_16x16x32_bf16 v[92:95], v[156:159], v[188:191], v[92:95]
	v_mfma_f32_16x16x32_bf16 v[88:91], v[164:167], v[188:191], v[88:91]
	v_mfma_f32_16x16x32_bf16 v[76:79], v[156:159], v[196:199], v[76:79]
	v_mfma_f32_16x16x32_bf16 v[72:75], v[164:167], v[196:199], v[72:75]
	s_setprio 0
	s_barrier
	s_add_i32 s28, 0, 0x1c000
	s_add_i32 s29, s58, s31
	v_add_u32_e32 v151, s28, v145
	s_mov_b32 m0, s29
	ds_read_b128 v[200:203], v151
	ds_read_b128 v[204:207], v151 offset:1024
	ds_read_b128 v[208:211], v151 offset:2048
	ds_read_b128 v[212:215], v151 offset:3072
	global_load_lds_dwordx4 v132, s[80:81]
	s_add_i32 m0, s29, 0x2000
	s_nop 0
	global_load_lds_dwordx4 v128, s[80:81]
	s_waitcnt vmcnt(10)
	s_barrier
	s_waitcnt lgkmcnt(0)
	s_setprio 1
	s_waitcnt lgkmcnt(0)
	v_mfma_f32_16x16x32_bf16 v[116:119], v[200:203], v[168:171], v[116:119]
	v_mfma_f32_16x16x32_bf16 v[112:115], v[208:211], v[168:171], v[112:115]
	v_mfma_f32_16x16x32_bf16 v[100:103], v[200:203], v[176:179], v[100:103]
	v_mfma_f32_16x16x32_bf16 v[96:99], v[208:211], v[176:179], v[96:99]
	v_mfma_f32_16x16x32_bf16 v[84:87], v[200:203], v[184:187], v[84:87]
	v_mfma_f32_16x16x32_bf16 v[80:83], v[208:211], v[184:187], v[80:83]
	v_mfma_f32_16x16x32_bf16 v[68:71], v[200:203], v[192:195], v[68:71]
	v_mfma_f32_16x16x32_bf16 v[64:67], v[208:211], v[192:195], v[64:67]
	v_mfma_f32_16x16x32_bf16 v[116:119], v[204:207], v[172:175], v[116:119]
	v_mfma_f32_16x16x32_bf16 v[112:115], v[212:215], v[172:175], v[112:115]
	v_mfma_f32_16x16x32_bf16 v[100:103], v[204:207], v[180:183], v[100:103]
	v_mfma_f32_16x16x32_bf16 v[96:99], v[212:215], v[180:183], v[96:99]
	v_mfma_f32_16x16x32_bf16 v[84:87], v[204:207], v[188:191], v[84:87]
	v_mfma_f32_16x16x32_bf16 v[80:83], v[212:215], v[188:191], v[80:83]
	v_mfma_f32_16x16x32_bf16 v[68:71], v[204:207], v[196:199], v[68:71]
	v_mfma_f32_16x16x32_bf16 v[64:67], v[212:215], v[196:199], v[64:67]
	s_setprio 0
	s_mov_b32 m0, s45
	s_barrier
	ds_read_b128 v[168:171], v149 offset:49152
	ds_read_b128 v[172:175], v149 offset:50176
	ds_read_b128 v[176:179], v149 offset:51200
	ds_read_b128 v[180:183], v149 offset:52224
	ds_read_b128 v[184:187], v149 offset:53248
	ds_read_b128 v[188:191], v149 offset:54272
	ds_read_b128 v[192:195], v149 offset:55296
	ds_read_b128 v[196:199], v149 offset:56320
	global_load_lds_dwordx4 v134, s[82:83]
	s_mov_b32 m0, s46
	s_nop 0
	global_load_lds_dwordx4 v130, s[82:83]
	s_barrier
	s_waitcnt lgkmcnt(0)
	s_setprio 1
	s_waitcnt lgkmcnt(0)
	v_mfma_f32_16x16x32_bf16 v[60:63], v[152:155], v[168:171], v[60:63]
	v_mfma_f32_16x16x32_bf16 v[56:59], v[160:163], v[168:171], v[56:59]
	v_mfma_f32_16x16x32_bf16 v[44:47], v[152:155], v[176:179], v[44:47]
	v_mfma_f32_16x16x32_bf16 v[40:43], v[160:163], v[176:179], v[40:43]
	v_mfma_f32_16x16x32_bf16 v[28:31], v[152:155], v[184:187], v[28:31]
	v_mfma_f32_16x16x32_bf16 v[24:27], v[160:163], v[184:187], v[24:27]
	v_mfma_f32_16x16x32_bf16 v[12:15], v[152:155], v[192:195], v[12:15]
	v_mfma_f32_16x16x32_bf16 v[8:11], v[160:163], v[192:195], v[8:11]
	v_mfma_f32_16x16x32_bf16 v[60:63], v[156:159], v[172:175], v[60:63]
	v_mfma_f32_16x16x32_bf16 v[56:59], v[164:167], v[172:175], v[56:59]
	v_mfma_f32_16x16x32_bf16 v[44:47], v[156:159], v[180:183], v[44:47]
	v_mfma_f32_16x16x32_bf16 v[40:43], v[164:167], v[180:183], v[40:43]
	v_mfma_f32_16x16x32_bf16 v[28:31], v[156:159], v[188:191], v[28:31]
	v_mfma_f32_16x16x32_bf16 v[24:27], v[164:167], v[188:191], v[24:27]
	v_mfma_f32_16x16x32_bf16 v[12:15], v[156:159], v[196:199], v[12:15]
	v_mfma_f32_16x16x32_bf16 v[8:11], v[164:167], v[196:199], v[8:11]
	s_setprio 0
	s_barrier
	s_add_u32 s26, s26, 0x40080
	s_addc_u32 s27, s27, 0
	s_add_i32 s28, s28, s31
	s_mov_b32 m0, s28
	s_nop 0
	global_load_lds_dwordx4 v132, s[26:27]
	s_add_i32 m0, s28, 0x2000
	s_nop 0
	global_load_lds_dwordx4 v128, s[26:27]
	s_waitcnt vmcnt(8)
	s_barrier
	s_setprio 1
	v_mfma_f32_16x16x32_bf16 v[52:55], v[200:203], v[168:171], v[52:55]
	v_mfma_f32_16x16x32_bf16 v[48:51], v[208:211], v[168:171], v[48:51]
	v_mfma_f32_16x16x32_bf16 v[36:39], v[200:203], v[176:179], v[36:39]
	v_mfma_f32_16x16x32_bf16 v[32:35], v[208:211], v[176:179], v[32:35]
	v_mfma_f32_16x16x32_bf16 v[20:23], v[200:203], v[184:187], v[20:23]
	v_mfma_f32_16x16x32_bf16 v[16:19], v[208:211], v[184:187], v[16:19]
	v_mfma_f32_16x16x32_bf16 v[4:7], v[200:203], v[192:195], v[4:7]
	v_mfma_f32_16x16x32_bf16 v[0:3], v[208:211], v[192:195], v[0:3]
	v_mfma_f32_16x16x32_bf16 v[52:55], v[204:207], v[172:175], v[52:55]
	v_mfma_f32_16x16x32_bf16 v[48:51], v[212:215], v[172:175], v[48:51]
	v_mfma_f32_16x16x32_bf16 v[36:39], v[204:207], v[180:183], v[36:39]
	v_mfma_f32_16x16x32_bf16 v[32:35], v[212:215], v[180:183], v[32:35]
	v_mfma_f32_16x16x32_bf16 v[20:23], v[204:207], v[188:191], v[20:23]
	v_mfma_f32_16x16x32_bf16 v[16:19], v[212:215], v[188:191], v[16:19]
	v_mfma_f32_16x16x32_bf16 v[4:7], v[204:207], v[196:199], v[4:7]
	v_mfma_f32_16x16x32_bf16 v[0:3], v[212:215], v[196:199], v[0:3]
	s_setprio 0
	s_add_i32 s57, s57, 2
	s_add_u32 s20, s20, 0x100
	s_addc_u32 s21, s21, 0
	s_add_u32 s55, s55, 0x100
	s_addc_u32 s56, s56, 0
	s_cmp_gt_u32 s57, 13
	s_barrier
	s_cbranch_scc0 .LBB0_893
	s_cmpk_gt_u32 s30, 0xff
	s_cbranch_scc1 .Lg893_nox
	s_barrier

.Lg973_noy:
	ds_read_b128 v[146:149], v203
	ds_read_b128 v[150:153], v203 offset:1024
	ds_read_b128 v[154:157], v203 offset:2048
	ds_read_b128 v[158:161], v203 offset:3072
	s_add_u32 s22, s20, 0x100
	s_addc_u32 s23, s21, 0
	s_cmp_eq_u32 s56, 40
	s_cselect_b32 s27, s5, s23
	s_cselect_b32 s26, s4, s22
	s_cselect_b32 s25, s7, s55
	s_cselect_b32 s24, s6, s54
	s_add_i32 m0, s37, 0xc000
	ds_read_b128 v[162:165], v204
	ds_read_b128 v[166:169], v204 offset:1024
	ds_read_b128 v[170:173], v204 offset:2048
	ds_read_b128 v[174:177], v204 offset:3072
	ds_read_b128 v[178:181], v204 offset:4096
	ds_read_b128 v[182:185], v204 offset:5120
	ds_read_b128 v[186:189], v204 offset:6144
	ds_read_b128 v[190:193], v204 offset:7168
	global_load_lds_dwordx4 v138, s[20:21]
	s_add_i32 m0, s37, 0xe000
	s_nop 0
	global_load_lds_dwordx4 v140, s[20:21]
	s_waitcnt lgkmcnt(8)
	s_barrier
	s_waitcnt lgkmcnt(0)
	s_setprio 1
	s_waitcnt lgkmcnt(0)
	v_mfma_f32_16x16x32_bf16 v[124:127], v[146:149], v[162:165], 0
	v_mfma_f32_16x16x32_bf16 v[120:123], v[154:157], v[162:165], 0
	v_mfma_f32_16x16x32_bf16 v[108:111], v[146:149], v[170:173], 0
	v_mfma_f32_16x16x32_bf16 v[104:107], v[154:157], v[170:173], 0
	v_mfma_f32_16x16x32_bf16 v[92:95], v[146:149], v[178:181], 0
	v_mfma_f32_16x16x32_bf16 v[88:91], v[154:157], v[178:181], 0
	v_mfma_f32_16x16x32_bf16 v[76:79], v[146:149], v[186:189], 0
	v_mfma_f32_16x16x32_bf16 v[72:75], v[154:157], v[186:189], 0
	v_mfma_f32_16x16x32_bf16 v[124:127], v[150:153], v[166:169], v[124:127]
	v_mfma_f32_16x16x32_bf16 v[120:123], v[158:161], v[166:169], v[120:123]
	v_mfma_f32_16x16x32_bf16 v[108:111], v[150:153], v[174:177], v[108:111]
	v_mfma_f32_16x16x32_bf16 v[104:107], v[158:161], v[174:177], v[104:107]
	v_mfma_f32_16x16x32_bf16 v[92:95], v[150:153], v[182:185], v[92:95]
	v_mfma_f32_16x16x32_bf16 v[88:91], v[158:161], v[182:185], v[88:91]
	v_mfma_f32_16x16x32_bf16 v[76:79], v[150:153], v[190:193], v[76:79]
	v_mfma_f32_16x16x32_bf16 v[72:75], v[158:161], v[190:193], v[72:75]
	s_setprio 0
	s_barrier
	s_add_i32 s20, s47, s36
	s_add_u32 s80, s24, 0x80
	s_addc_u32 s81, s25, 0
	s_mov_b32 m0, s20
	ds_read_b128 v[194:197], v205
	ds_read_b128 v[208:211], v205 offset:1024
	ds_read_b128 v[212:215], v205 offset:2048
	ds_read_b128 v[216:219], v205 offset:3072
	global_load_lds_dwordx4 v130, s[24:25]
	s_add_i32 m0, s20, 0x2000
	s_nop 0
	global_load_lds_dwordx4 v134, s[24:25]
	s_waitcnt vmcnt(10)
	s_barrier
	s_waitcnt lgkmcnt(0)
	s_setprio 1
	s_waitcnt lgkmcnt(0)
	v_mfma_f32_16x16x32_bf16 v[116:119], v[194:197], v[162:165], 0
	v_mfma_f32_16x16x32_bf16 v[112:115], v[212:215], v[162:165], 0
	v_mfma_f32_16x16x32_bf16 v[100:103], v[194:197], v[170:173], 0
	v_mfma_f32_16x16x32_bf16 v[96:99], v[212:215], v[170:173], 0
	v_mfma_f32_16x16x32_bf16 v[84:87], v[194:197], v[178:181], 0
	v_mfma_f32_16x16x32_bf16 v[80:83], v[212:215], v[178:181], 0
	v_mfma_f32_16x16x32_bf16 v[68:71], v[194:197], v[186:189], 0
	v_mfma_f32_16x16x32_bf16 v[64:67], v[212:215], v[186:189], 0
	v_mfma_f32_16x16x32_bf16 v[116:119], v[208:211], v[166:169], v[116:119]
	v_mfma_f32_16x16x32_bf16 v[112:115], v[216:219], v[166:169], v[112:115]
	v_mfma_f32_16x16x32_bf16 v[100:103], v[208:211], v[174:177], v[100:103]
	v_mfma_f32_16x16x32_bf16 v[96:99], v[216:219], v[174:177], v[96:99]
	v_mfma_f32_16x16x32_bf16 v[84:87], v[208:211], v[182:185], v[84:87]
	v_mfma_f32_16x16x32_bf16 v[80:83], v[216:219], v[182:185], v[80:83]
	v_mfma_f32_16x16x32_bf16 v[68:71], v[208:211], v[190:193], v[68:71]
	v_mfma_f32_16x16x32_bf16 v[64:67], v[216:219], v[190:193], v[64:67]
	s_setprio 0
	s_mov_b32 m0, s37
	s_add_u32 s82, s26, 0x80
	s_addc_u32 s83, s27, 0
	s_barrier
	ds_read_b128 v[162:165], v204 offset:16384
	ds_read_b128 v[166:169], v204 offset:17408
	ds_read_b128 v[170:173], v204 offset:18432
	ds_read_b128 v[174:177], v204 offset:19456
	ds_read_b128 v[178:181], v204 offset:20480
	ds_read_b128 v[182:185], v204 offset:21504
	ds_read_b128 v[186:189], v204 offset:22528
	ds_read_b128 v[190:193], v204 offset:23552
	global_load_lds_dwordx4 v128, s[26:27]
	s_mov_b32 m0, s38
	s_nop 0
	global_load_lds_dwordx4 v132, s[26:27]
	s_barrier
	s_waitcnt lgkmcnt(0)
	s_setprio 1
	s_waitcnt lgkmcnt(0)
	v_mfma_f32_16x16x32_bf16 v[60:63], v[146:149], v[162:165], 0
	v_mfma_f32_16x16x32_bf16 v[56:59], v[154:157], v[162:165], 0
	v_mfma_f32_16x16x32_bf16 v[44:47], v[146:149], v[170:173], 0
	v_mfma_f32_16x16x32_bf16 v[40:43], v[154:157], v[170:173], 0
	v_mfma_f32_16x16x32_bf16 v[28:31], v[146:149], v[178:181], 0
	v_mfma_f32_16x16x32_bf16 v[24:27], v[154:157], v[178:181], 0
	v_mfma_f32_16x16x32_bf16 v[12:15], v[146:149], v[186:189], 0
	v_mfma_f32_16x16x32_bf16 v[8:11], v[154:157], v[186:189], 0
	v_mfma_f32_16x16x32_bf16 v[60:63], v[150:153], v[166:169], v[60:63]
	v_mfma_f32_16x16x32_bf16 v[56:59], v[158:161], v[166:169], v[56:59]
	v_mfma_f32_16x16x32_bf16 v[44:47], v[150:153], v[174:177], v[44:47]
	v_mfma_f32_16x16x32_bf16 v[40:43], v[158:161], v[174:177], v[40:43]
	v_mfma_f32_16x16x32_bf16 v[28:31], v[150:153], v[182:185], v[28:31]
	v_mfma_f32_16x16x32_bf16 v[24:27], v[158:161], v[182:185], v[24:27]
	v_mfma_f32_16x16x32_bf16 v[12:15], v[150:153], v[190:193], v[12:15]
	v_mfma_f32_16x16x32_bf16 v[8:11], v[158:161], v[190:193], v[8:11]
	s_setprio 0
	s_barrier
	s_add_u32 s20, s24, 0xb0000
	s_addc_u32 s21, s25, 0
	s_add_i32 s57, s48, s36
	s_mov_b32 m0, s57
	s_nop 0
	global_load_lds_dwordx4 v130, s[20:21]
	s_add_i32 m0, s57, 0x2000
	s_nop 0
	global_load_lds_dwordx4 v134, s[20:21]
	s_waitcnt vmcnt(8)
	s_barrier
	s_setprio 1
	v_mfma_f32_16x16x32_bf16 v[52:55], v[194:197], v[162:165], 0
	v_mfma_f32_16x16x32_bf16 v[48:51], v[212:215], v[162:165], 0
	v_mfma_f32_16x16x32_bf16 v[36:39], v[194:197], v[170:173], 0
	v_mfma_f32_16x16x32_bf16 v[32:35], v[212:215], v[170:173], 0
	v_mfma_f32_16x16x32_bf16 v[20:23], v[194:197], v[178:181], 0
	v_mfma_f32_16x16x32_bf16 v[16:19], v[212:215], v[178:181], 0
	v_mfma_f32_16x16x32_bf16 v[4:7], v[194:197], v[186:189], 0
	v_mfma_f32_16x16x32_bf16 v[0:3], v[212:215], v[186:189], 0
	v_mfma_f32_16x16x32_bf16 v[52:55], v[208:211], v[166:169], v[52:55]
	v_mfma_f32_16x16x32_bf16 v[48:51], v[216:219], v[166:169], v[48:51]
	v_mfma_f32_16x16x32_bf16 v[36:39], v[208:211], v[174:177], v[36:39]
	v_mfma_f32_16x16x32_bf16 v[32:35], v[216:219], v[174:177], v[32:35]
	v_mfma_f32_16x16x32_bf16 v[20:23], v[208:211], v[182:185], v[20:23]
	v_mfma_f32_16x16x32_bf16 v[16:19], v[216:219], v[182:185], v[16:19]
	v_mfma_f32_16x16x32_bf16 v[4:7], v[208:211], v[190:193], v[4:7]
	v_mfma_f32_16x16x32_bf16 v[0:3], v[216:219], v[190:193], v[0:3]
	s_setprio 0
	s_add_i32 s57, 0, 0x18000
	v_add_u32_e32 v158, s57, v201
	s_barrier
	s_branch .Lg973_mid
.LBB0_973:
	ds_read_b128 v[146:149], v203
	ds_read_b128 v[150:153], v203 offset:1024
	ds_read_b128 v[154:157], v203 offset:2048
	ds_read_b128 v[158:161], v203 offset:3072
	s_add_u32 s22, s20, 0x100
	s_addc_u32 s23, s21, 0
	s_cmp_eq_u32 s56, 40
	s_cselect_b32 s27, s5, s23
	s_cselect_b32 s26, s4, s22
	s_cselect_b32 s25, s7, s55
	s_cselect_b32 s24, s6, s54
	s_add_i32 m0, s37, 0xc000
	ds_read_b128 v[162:165], v204
	ds_read_b128 v[166:169], v204 offset:1024
	ds_read_b128 v[170:173], v204 offset:2048
	ds_read_b128 v[174:177], v204 offset:3072
	ds_read_b128 v[178:181], v204 offset:4096
	ds_read_b128 v[182:185], v204 offset:5120
	ds_read_b128 v[186:189], v204 offset:6144
	ds_read_b128 v[190:193], v204 offset:7168
	global_load_lds_dwordx4 v138, s[20:21]
	s_add_i32 m0, s37, 0xe000
	s_nop 0
	global_load_lds_dwordx4 v140, s[20:21]
	s_waitcnt lgkmcnt(8)
	s_barrier
	s_waitcnt lgkmcnt(0)
	s_setprio 1
	s_waitcnt lgkmcnt(0)
	v_mfma_f32_16x16x32_bf16 v[124:127], v[146:149], v[162:165], v[124:127]
	v_mfma_f32_16x16x32_bf16 v[120:123], v[154:157], v[162:165], v[120:123]
	v_mfma_f32_16x16x32_bf16 v[108:111], v[146:149], v[170:173], v[108:111]
	v_mfma_f32_16x16x32_bf16 v[104:107], v[154:157], v[170:173], v[104:107]
	v_mfma_f32_16x16x32_bf16 v[92:95], v[146:149], v[178:181], v[92:95]
	v_mfma_f32_16x16x32_bf16 v[88:91], v[154:157], v[178:181], v[88:91]
	v_mfma_f32_16x16x32_bf16 v[76:79], v[146:149], v[186:189], v[76:79]
	v_mfma_f32_16x16x32_bf16 v[72:75], v[154:157], v[186:189], v[72:75]
	v_mfma_f32_16x16x32_bf16 v[124:127], v[150:153], v[166:169], v[124:127]
	v_mfma_f32_16x16x32_bf16 v[120:123], v[158:161], v[166:169], v[120:123]
	v_mfma_f32_16x16x32_bf16 v[108:111], v[150:153], v[174:177], v[108:111]
	v_mfma_f32_16x16x32_bf16 v[104:107], v[158:161], v[174:177], v[104:107]
	v_mfma_f32_16x16x32_bf16 v[92:95], v[150:153], v[182:185], v[92:95]
	v_mfma_f32_16x16x32_bf16 v[88:91], v[158:161], v[182:185], v[88:91]
	v_mfma_f32_16x16x32_bf16 v[76:79], v[150:153], v[190:193], v[76:79]
	v_mfma_f32_16x16x32_bf16 v[72:75], v[158:161], v[190:193], v[72:75]
	s_setprio 0
	s_barrier
	s_add_i32 s20, s47, s36
	s_add_u32 s80, s24, 0x80
	s_addc_u32 s81, s25, 0
	s_mov_b32 m0, s20
	ds_read_b128 v[194:197], v205
	ds_read_b128 v[208:211], v205 offset:1024
	ds_read_b128 v[212:215], v205 offset:2048
	ds_read_b128 v[216:219], v205 offset:3072
	global_load_lds_dwordx4 v130, s[24:25]
	s_add_i32 m0, s20, 0x2000
	s_nop 0
	global_load_lds_dwordx4 v134, s[24:25]
	s_waitcnt vmcnt(10)
	s_barrier
	s_waitcnt lgkmcnt(0)
	s_setprio 1
	s_waitcnt lgkmcnt(0)
	v_mfma_f32_16x16x32_bf16 v[116:119], v[194:197], v[162:165], v[116:119]
	v_mfma_f32_16x16x32_bf16 v[112:115], v[212:215], v[162:165], v[112:115]
	v_mfma_f32_16x16x32_bf16 v[100:103], v[194:197], v[170:173], v[100:103]
	v_mfma_f32_16x16x32_bf16 v[96:99], v[212:215], v[170:173], v[96:99]
	v_mfma_f32_16x16x32_bf16 v[84:87], v[194:197], v[178:181], v[84:87]
	v_mfma_f32_16x16x32_bf16 v[80:83], v[212:215], v[178:181], v[80:83]
	v_mfma_f32_16x16x32_bf16 v[68:71], v[194:197], v[186:189], v[68:71]
	v_mfma_f32_16x16x32_bf16 v[64:67], v[212:215], v[186:189], v[64:67]
	v_mfma_f32_16x16x32_bf16 v[116:119], v[208:211], v[166:169], v[116:119]
	v_mfma_f32_16x16x32_bf16 v[112:115], v[216:219], v[166:169], v[112:115]
	v_mfma_f32_16x16x32_bf16 v[100:103], v[208:211], v[174:177], v[100:103]
	v_mfma_f32_16x16x32_bf16 v[96:99], v[216:219], v[174:177], v[96:99]
	v_mfma_f32_16x16x32_bf16 v[84:87], v[208:211], v[182:185], v[84:87]
	v_mfma_f32_16x16x32_bf16 v[80:83], v[216:219], v[182:185], v[80:83]
	v_mfma_f32_16x16x32_bf16 v[68:71], v[208:211], v[190:193], v[68:71]
	v_mfma_f32_16x16x32_bf16 v[64:67], v[216:219], v[190:193], v[64:67]
	s_setprio 0
	s_mov_b32 m0, s37
	s_add_u32 s82, s26, 0x80
	s_addc_u32 s83, s27, 0
	s_barrier
	ds_read_b128 v[162:165], v204 offset:16384
	ds_read_b128 v[166:169], v204 offset:17408
	ds_read_b128 v[170:173], v204 offset:18432
	ds_read_b128 v[174:177], v204 offset:19456
	ds_read_b128 v[178:181], v204 offset:20480
	ds_read_b128 v[182:185], v204 offset:21504
	ds_read_b128 v[186:189], v204 offset:22528
	ds_read_b128 v[190:193], v204 offset:23552
	global_load_lds_dwordx4 v128, s[26:27]
	s_mov_b32 m0, s38
	s_nop 0
	global_load_lds_dwordx4 v132, s[26:27]
	s_barrier
	s_waitcnt lgkmcnt(0)
	s_setprio 1
	s_waitcnt lgkmcnt(0)
	v_mfma_f32_16x16x32_bf16 v[60:63], v[146:149], v[162:165], v[60:63]
	v_mfma_f32_16x16x32_bf16 v[56:59], v[154:157], v[162:165], v[56:59]
	v_mfma_f32_16x16x32_bf16 v[44:47], v[146:149], v[170:173], v[44:47]
	v_mfma_f32_16x16x32_bf16 v[40:43], v[154:157], v[170:173], v[40:43]
	v_mfma_f32_16x16x32_bf16 v[28:31], v[146:149], v[178:181], v[28:31]
	v_mfma_f32_16x16x32_bf16 v[24:27], v[154:157], v[178:181], v[24:27]
	v_mfma_f32_16x16x32_bf16 v[12:15], v[146:149], v[186:189], v[12:15]
	v_mfma_f32_16x16x32_bf16 v[8:11], v[154:157], v[186:189], v[8:11]
	v_mfma_f32_16x16x32_bf16 v[60:63], v[150:153], v[166:169], v[60:63]
	v_mfma_f32_16x16x32_bf16 v[56:59], v[158:161], v[166:169], v[56:59]
	v_mfma_f32_16x16x32_bf16 v[44:47], v[150:153], v[174:177], v[44:47]
	v_mfma_f32_16x16x32_bf16 v[40:43], v[158:161], v[174:177], v[40:43]
	v_mfma_f32_16x16x32_bf16 v[28:31], v[150:153], v[182:185], v[28:31]
	v_mfma_f32_16x16x32_bf16 v[24:27], v[158:161], v[182:185], v[24:27]
	v_mfma_f32_16x16x32_bf16 v[12:15], v[150:153], v[190:193], v[12:15]
	v_mfma_f32_16x16x32_bf16 v[8:11], v[158:161], v[190:193], v[8:11]
	s_setprio 0
	s_barrier
	s_add_u32 s20, s24, 0xb0000
	s_addc_u32 s21, s25, 0
	s_add_i32 s57, s48, s36
	s_mov_b32 m0, s57
	s_nop 0
	global_load_lds_dwordx4 v130, s[20:21]
	s_add_i32 m0, s57, 0x2000
	s_nop 0
	global_load_lds_dwordx4 v134, s[20:21]
	s_waitcnt vmcnt(8)
	s_barrier
	s_setprio 1
	v_mfma_f32_16x16x32_bf16 v[52:55], v[194:197], v[162:165], v[52:55]
	v_mfma_f32_16x16x32_bf16 v[48:51], v[212:215], v[162:165], v[48:51]
	v_mfma_f32_16x16x32_bf16 v[36:39], v[194:197], v[170:173], v[36:39]
	v_mfma_f32_16x16x32_bf16 v[32:35], v[212:215], v[170:173], v[32:35]
	v_mfma_f32_16x16x32_bf16 v[20:23], v[194:197], v[178:181], v[20:23]
	v_mfma_f32_16x16x32_bf16 v[16:19], v[212:215], v[178:181], v[16:19]
	v_mfma_f32_16x16x32_bf16 v[4:7], v[194:197], v[186:189], v[4:7]
	v_mfma_f32_16x16x32_bf16 v[0:3], v[212:215], v[186:189], v[0:3]
	v_mfma_f32_16x16x32_bf16 v[52:55], v[208:211], v[166:169], v[52:55]
	v_mfma_f32_16x16x32_bf16 v[48:51], v[216:219], v[166:169], v[48:51]
	v_mfma_f32_16x16x32_bf16 v[36:39], v[208:211], v[174:177], v[36:39]
	v_mfma_f32_16x16x32_bf16 v[32:35], v[216:219], v[174:177], v[32:35]
	v_mfma_f32_16x16x32_bf16 v[20:23], v[208:211], v[182:185], v[20:23]
	v_mfma_f32_16x16x32_bf16 v[16:19], v[216:219], v[182:185], v[16:19]
	v_mfma_f32_16x16x32_bf16 v[4:7], v[208:211], v[190:193], v[4:7]
	v_mfma_f32_16x16x32_bf16 v[0:3], v[216:219], v[190:193], v[0:3]
	s_setprio 0
	s_add_i32 s57, 0, 0x18000
	v_add_u32_e32 v158, s57, v201
	s_barrier
.Lg973_mid:
	ds_read_b128 v[146:149], v158
	ds_read_b128 v[150:153], v158 offset:1024
	ds_read_b128 v[154:157], v158 offset:2048
	ds_read_b128 v[158:161], v158 offset:3072
	s_add_u32 s20, s26, 0xb0000
	s_addc_u32 s21, s27, 0
	s_mov_b32 m0, s39
	ds_read_b128 v[162:165], v204 offset:32768
	ds_read_b128 v[166:169], v204 offset:33792
	ds_read_b128 v[170:173], v204 offset:34816
	ds_read_b128 v[174:177], v204 offset:35840
	ds_read_b128 v[178:181], v204 offset:36864
	ds_read_b128 v[182:185], v204 offset:37888
	ds_read_b128 v[186:189], v204 offset:38912
	ds_read_b128 v[190:193], v204 offset:39936
	global_load_lds_dwordx4 v128, s[20:21]
	s_mov_b32 m0, s40
	s_nop 0
	global_load_lds_dwordx4 v132, s[20:21]
	s_waitcnt lgkmcnt(8)
	s_barrier
	s_waitcnt lgkmcnt(0)
	s_setprio 1
	s_waitcnt lgkmcnt(0)
	v_mfma_f32_16x16x32_bf16 v[124:127], v[146:149], v[162:165], v[124:127]
	v_mfma_f32_16x16x32_bf16 v[120:123], v[154:157], v[162:165], v[120:123]
	v_mfma_f32_16x16x32_bf16 v[108:111], v[146:149], v[170:173], v[108:111]
	v_mfma_f32_16x16x32_bf16 v[104:107], v[154:157], v[170:173], v[104:107]
	v_mfma_f32_16x16x32_bf16 v[92:95], v[146:149], v[178:181], v[92:95]
	v_mfma_f32_16x16x32_bf16 v[88:91], v[154:157], v[178:181], v[88:91]
	v_mfma_f32_16x16x32_bf16 v[76:79], v[146:149], v[186:189], v[76:79]
	v_mfma_f32_16x16x32_bf16 v[72:75], v[154:157], v[186:189], v[72:75]
	v_mfma_f32_16x16x32_bf16 v[124:127], v[150:153], v[166:169], v[124:127]
	v_mfma_f32_16x16x32_bf16 v[120:123], v[158:161], v[166:169], v[120:123]
	v_mfma_f32_16x16x32_bf16 v[108:111], v[150:153], v[174:177], v[108:111]
	v_mfma_f32_16x16x32_bf16 v[104:107], v[158:161], v[174:177], v[104:107]
	v_mfma_f32_16x16x32_bf16 v[92:95], v[150:153], v[182:185], v[92:95]
	v_mfma_f32_16x16x32_bf16 v[88:91], v[158:161], v[182:185], v[88:91]
	v_mfma_f32_16x16x32_bf16 v[76:79], v[150:153], v[190:193], v[76:79]
	v_mfma_f32_16x16x32_bf16 v[72:75], v[158:161], v[190:193], v[72:75]
	s_setprio 0
	s_barrier
	s_add_i32 s26, 0, 0x1c000
	s_add_i32 s20, s57, s36
	v_add_u32_e32 v216, s26, v201
	s_mov_b32 m0, s20
	ds_read_b128 v[194:197], v216
	ds_read_b128 v[208:211], v216 offset:1024
	ds_read_b128 v[212:215], v216 offset:2048
	ds_read_b128 v[216:219], v216 offset:3072
	global_load_lds_dwordx4 v130, s[80:81]
	s_add_i32 m0, s20, 0x2000
	s_nop 0
	global_load_lds_dwordx4 v134, s[80:81]
	s_waitcnt vmcnt(10)
	s_barrier
	s_waitcnt lgkmcnt(0)
	s_setprio 1
	s_waitcnt lgkmcnt(0)
	v_mfma_f32_16x16x32_bf16 v[116:119], v[194:197], v[162:165], v[116:119]
	v_mfma_f32_16x16x32_bf16 v[112:115], v[212:215], v[162:165], v[112:115]
	v_mfma_f32_16x16x32_bf16 v[100:103], v[194:197], v[170:173], v[100:103]
	v_mfma_f32_16x16x32_bf16 v[96:99], v[212:215], v[170:173], v[96:99]
	v_mfma_f32_16x16x32_bf16 v[84:87], v[194:197], v[178:181], v[84:87]
	v_mfma_f32_16x16x32_bf16 v[80:83], v[212:215], v[178:181], v[80:83]
	v_mfma_f32_16x16x32_bf16 v[68:71], v[194:197], v[186:189], v[68:71]
	v_mfma_f32_16x16x32_bf16 v[64:67], v[212:215], v[186:189], v[64:67]
	v_mfma_f32_16x16x32_bf16 v[116:119], v[208:211], v[166:169], v[116:119]
	v_mfma_f32_16x16x32_bf16 v[112:115], v[216:219], v[166:169], v[112:115]
	v_mfma_f32_16x16x32_bf16 v[100:103], v[208:211], v[174:177], v[100:103]
	v_mfma_f32_16x16x32_bf16 v[96:99], v[216:219], v[174:177], v[96:99]
	v_mfma_f32_16x16x32_bf16 v[84:87], v[208:211], v[182:185], v[84:87]
	v_mfma_f32_16x16x32_bf16 v[80:83], v[216:219], v[182:185], v[80:83]
	v_mfma_f32_16x16x32_bf16 v[68:71], v[208:211], v[190:193], v[68:71]
	v_mfma_f32_16x16x32_bf16 v[64:67], v[216:219], v[190:193], v[64:67]
	s_setprio 0
	s_mov_b32 m0, s42
	s_barrier
	ds_read_b128 v[162:165], v204 offset:49152
	ds_read_b128 v[166:169], v204 offset:50176
	ds_read_b128 v[170:173], v204 offset:51200
	ds_read_b128 v[174:177], v204 offset:52224
	ds_read_b128 v[178:181], v204 offset:53248
	ds_read_b128 v[182:185], v204 offset:54272
	ds_read_b128 v[186:189], v204 offset:55296
	ds_read_b128 v[190:193], v204 offset:56320
	global_load_lds_dwordx4 v128, s[82:83]
	s_mov_b32 m0, s43
	s_nop 0
	global_load_lds_dwordx4 v132, s[82:83]
	s_barrier
	s_waitcnt lgkmcnt(0)
	s_setprio 1
	s_waitcnt lgkmcnt(0)
	v_mfma_f32_16x16x32_bf16 v[60:63], v[146:149], v[162:165], v[60:63]
	v_mfma_f32_16x16x32_bf16 v[56:59], v[154:157], v[162:165], v[56:59]
	v_mfma_f32_16x16x32_bf16 v[44:47], v[146:149], v[170:173], v[44:47]
	v_mfma_f32_16x16x32_bf16 v[40:43], v[154:157], v[170:173], v[40:43]
	v_mfma_f32_16x16x32_bf16 v[28:31], v[146:149], v[178:181], v[28:31]
	v_mfma_f32_16x16x32_bf16 v[24:27], v[154:157], v[178:181], v[24:27]
	v_mfma_f32_16x16x32_bf16 v[12:15], v[146:149], v[186:189], v[12:15]
	v_mfma_f32_16x16x32_bf16 v[8:11], v[154:157], v[186:189], v[8:11]
	v_mfma_f32_16x16x32_bf16 v[60:63], v[150:153], v[166:169], v[60:63]
	v_mfma_f32_16x16x32_bf16 v[56:59], v[158:161], v[166:169], v[56:59]
	v_mfma_f32_16x16x32_bf16 v[44:47], v[150:153], v[174:177], v[44:47]
	v_mfma_f32_16x16x32_bf16 v[40:43], v[158:161], v[174:177], v[40:43]
	v_mfma_f32_16x16x32_bf16 v[28:31], v[150:153], v[182:185], v[28:31]
	v_mfma_f32_16x16x32_bf16 v[24:27], v[158:161], v[182:185], v[24:27]
	v_mfma_f32_16x16x32_bf16 v[12:15], v[150:153], v[190:193], v[12:15]
	v_mfma_f32_16x16x32_bf16 v[8:11], v[158:161], v[190:193], v[8:11]
	s_setprio 0
	s_barrier
	s_add_u32 s20, s24, 0xb0080
	s_addc_u32 s21, s25, 0
	s_add_i32 s24, s26, s36
	s_mov_b32 m0, s24
	s_nop 0
	global_load_lds_dwordx4 v130, s[20:21]
	s_add_i32 m0, s24, 0x2000
	s_nop 0
	global_load_lds_dwordx4 v134, s[20:21]
	s_waitcnt vmcnt(8)
	s_barrier
	s_setprio 1
	v_mfma_f32_16x16x32_bf16 v[52:55], v[194:197], v[162:165], v[52:55]
	v_mfma_f32_16x16x32_bf16 v[48:51], v[212:215], v[162:165], v[48:51]
	v_mfma_f32_16x16x32_bf16 v[36:39], v[194:197], v[170:173], v[36:39]
	v_mfma_f32_16x16x32_bf16 v[32:35], v[212:215], v[170:173], v[32:35]
	v_mfma_f32_16x16x32_bf16 v[20:23], v[194:197], v[178:181], v[20:23]
	v_mfma_f32_16x16x32_bf16 v[16:19], v[212:215], v[178:181], v[16:19]
	v_mfma_f32_16x16x32_bf16 v[4:7], v[194:197], v[186:189], v[4:7]
	v_mfma_f32_16x16x32_bf16 v[0:3], v[212:215], v[186:189], v[0:3]
	v_mfma_f32_16x16x32_bf16 v[52:55], v[208:211], v[166:169], v[52:55]
	v_mfma_f32_16x16x32_bf16 v[48:51], v[216:219], v[166:169], v[48:51]
	v_mfma_f32_16x16x32_bf16 v[36:39], v[208:211], v[174:177], v[36:39]
	v_mfma_f32_16x16x32_bf16 v[32:35], v[216:219], v[174:177], v[32:35]
	v_mfma_f32_16x16x32_bf16 v[20:23], v[208:211], v[182:185], v[20:23]
	v_mfma_f32_16x16x32_bf16 v[16:19], v[216:219], v[182:185], v[16:19]
	v_mfma_f32_16x16x32_bf16 v[4:7], v[208:211], v[190:193], v[4:7]
	v_mfma_f32_16x16x32_bf16 v[0:3], v[216:219], v[190:193], v[0:3]
	s_setprio 0
	s_add_i32 s56, s56, 2
	s_add_u32 s54, s54, 0x100
	s_addc_u32 s55, s55, 0
	s_cmp_gt_u32 s56, 41
	s_mov_b64 s[20:21], s[22:23]
	s_barrier
	s_cbranch_scc0 .LBB0_973
	s_cmpk_gt_u32 s30, 0xff
	s_cbranch_scc1 .Lg973_nox
	s_barrier
